# k22
# speedup vs baseline: 1.1367x; 1.0064x over previous
.Lat_kb:
	s_add_u32 s88, s86, 1
	s_sub_u32 s89, s17, 1
	s_min_u32 s88, s88, s89
	s_lshl_b32 s89, s88, 17
	s_add_u32 s90, s78, s89
	s_addc_u32 s91, s79, 0
	global_load_dwordx4 a[224:227], v8, s[90:91]
	global_load_dwordx4 a[228:231], v9, s[90:91]
	global_load_dwordx4 a[232:235], v10, s[90:91]
	global_load_dwordx4 a[236:239], v11, s[90:91]
	s_lshl_b32 s89, s88, 7
	s_add_u32 s90, s80, s89
	s_addc_u32 s91, s81, 0
	global_load_dwordx4 a[240:243], v12, s[90:91]
	global_load_dwordx4 a[244:247], v13, s[90:91]
	global_load_dwordx4 a[248:251], v14, s[90:91]
	global_load_dwordx4 a[252:255], v15, s[90:91]
	s_add_u32 s88, s84, 31
	s_cmp_gt_u32 s85, s88
	s_cbranch_scc1 .Lat_skip
	v_add_u32_e32 v6, s87, v4
	v_add_u32_e32 v7, s87, v5
	ds_read_b128 a[32:35], v6 offset:0
	ds_read_b128 a[36:39], v6 offset:32
	ds_read_b128 a[40:43], v6 offset:64
	ds_read_b128 a[44:47], v6 offset:96
	ds_read_b128 a[48:51], v6 offset:8704
	ds_read_b128 a[52:55], v6 offset:8736
	ds_read_b128 a[56:59], v6 offset:8768
	ds_read_b128 a[60:63], v6 offset:8800
	ds_read_b128 a[64:67], v6 offset:128
	ds_read_b128 a[68:71], v6 offset:160
	ds_read_b128 a[72:75], v6 offset:192
	ds_read_b128 a[76:79], v6 offset:224
	ds_read_b128 a[80:83], v6 offset:8832
	ds_read_b128 a[84:87], v6 offset:8864
	ds_read_b128 a[88:91], v6 offset:8896
	ds_read_b128 a[92:95], v6 offset:8928
	s_add_u32 s88, s85, 63
	s_cmp_gt_u32 s88, s84
	s_cbranch_scc1 .Lat_diag
	s_waitcnt lgkmcnt(15)
	v_mfma_f32_32x32x16_bf16 v[192:207], a[32:35], a[0:3], 0
	s_waitcnt lgkmcnt(11)
	v_mfma_f32_32x32x16_bf16 v[208:223], a[48:51], a[0:3], 0
	s_waitcnt lgkmcnt(14)
	v_mfma_f32_32x32x16_bf16 v[192:207], a[36:39], a[4:7], v[192:207]
	s_waitcnt lgkmcnt(10)
	v_mfma_f32_32x32x16_bf16 v[208:223], a[52:55], a[4:7], v[208:223]
	s_waitcnt lgkmcnt(13)
	v_mfma_f32_32x32x16_bf16 v[192:207], a[40:43], a[8:11], v[192:207]
	s_waitcnt lgkmcnt(9)
	v_mfma_f32_32x32x16_bf16 v[208:223], a[56:59], a[8:11], v[208:223]
	s_waitcnt lgkmcnt(12)
	v_mfma_f32_32x32x16_bf16 v[192:207], a[44:47], a[12:15], v[192:207]
	s_waitcnt lgkmcnt(8)
	v_mfma_f32_32x32x16_bf16 v[208:223], a[60:63], a[12:15], v[208:223]
	s_waitcnt lgkmcnt(7)
	v_mfma_f32_32x32x16_bf16 v[32:47], a[64:67], a[16:19], 0
	s_waitcnt lgkmcnt(3)
	v_mfma_f32_32x32x16_bf16 v[48:63], a[80:83], a[16:19], 0
	s_waitcnt lgkmcnt(6)
	v_mfma_f32_32x32x16_bf16 v[32:47], a[68:71], a[20:23], v[32:47]
	s_waitcnt lgkmcnt(2)
	v_mfma_f32_32x32x16_bf16 v[48:63], a[84:87], a[20:23], v[48:63]
	ds_read2_b64 a[96:99], v7 offset0:0 offset1:2
	ds_read2_b64 a[100:103], v7 offset0:4 offset1:6
	ds_read2_b64 a[128:131], v7 offset0:8 offset1:10
	ds_read2_b64 a[132:135], v7 offset0:12 offset1:14
	v_add_u32_e32 v28, 0x1200, v7
	ds_read2_b64 a[104:107], v28 offset0:0 offset1:2
	ds_read2_b64 a[108:111], v28 offset0:4 offset1:6
	ds_read2_b64 a[136:139], v28 offset0:8 offset1:10
	ds_read2_b64 a[140:143], v28 offset0:12 offset1:14
	v_add_u32_e32 v28, 0x2400, v7
	ds_read2_b64 a[112:115], v28 offset0:0 offset1:2
	ds_read2_b64 a[116:119], v28 offset0:4 offset1:6
	ds_read2_b64 a[144:147], v28 offset0:8 offset1:10
	ds_read2_b64 a[148:151], v28 offset0:12 offset1:14
	v_add_u32_e32 v28, 0x3600, v7
	ds_read2_b64 a[120:123], v28 offset0:0 offset1:2
	ds_read2_b64 a[124:127], v28 offset0:4 offset1:6
	ds_read2_b64 a[152:155], v28 offset0:8 offset1:10
	ds_read2_b64 a[156:159], v28 offset0:12 offset1:14
	s_waitcnt lgkmcnt(15)
	v_mfma_f32_32x32x16_bf16 v[32:47], a[72:75], a[24:27], v[32:47]
	v_max3_f32 v224, v192, v193, v194
	v_max3_f32 v224, v224, v195, v196
	v_max3_f32 v224, v224, v197, v198
	v_max3_f32 v224, v224, v199, v200
	v_max3_f32 v224, v224, v201, v202
	v_max3_f32 v224, v224, v203, v204
	v_max3_f32 v224, v224, v205, v206
	v_max3_f32 v224, v224, v207, v208
	s_waitcnt lgkmcnt(15)
	v_mfma_f32_32x32x16_bf16 v[48:63], a[88:91], a[24:27], v[48:63]
	v_max3_f32 v224, v224, v209, v210
	v_max3_f32 v224, v224, v211, v212
	v_max3_f32 v224, v224, v213, v214
	v_max3_f32 v224, v224, v215, v216
	v_max3_f32 v224, v224, v217, v218
	v_max3_f32 v224, v224, v219, v220
	v_max3_f32 v224, v224, v221, v222
	v_max_f32_e32 v224, v224, v223
	s_waitcnt lgkmcnt(15)
	v_mfma_f32_32x32x16_bf16 v[32:47], a[76:79], a[28:31], v[32:47]
	v_mov_b32_e32 v225, v224
	s_nop 1
	v_permlane32_swap_b32_e32 v224, v225
	v_max3_f32 v226, v224, v225, v20
	v_sub_f32_e32 v228, v20, v226
	v_exp_f32_e32 v228, v228
	v_mov_b32_e32 v20, v226
	v_sub_f32_e32 v192, v192, v226
	s_waitcnt lgkmcnt(15)
	v_mfma_f32_32x32x16_bf16 v[48:63], a[92:95], a[28:31], v[48:63]
	v_sub_f32_e32 v193, v193, v226
	v_sub_f32_e32 v194, v194, v226
	v_sub_f32_e32 v195, v195, v226
	v_sub_f32_e32 v196, v196, v226
	v_sub_f32_e32 v197, v197, v226
	v_sub_f32_e32 v198, v198, v226
	v_sub_f32_e32 v199, v199, v226
	v_sub_f32_e32 v200, v200, v226
	v_sub_f32_e32 v201, v201, v226
	v_sub_f32_e32 v202, v202, v226
	v_sub_f32_e32 v203, v203, v226
	v_sub_f32_e32 v204, v204, v226
	v_sub_f32_e32 v205, v205, v226
	v_sub_f32_e32 v206, v206, v226
	v_sub_f32_e32 v207, v207, v226
	v_sub_f32_e32 v208, v208, v226
	v_sub_f32_e32 v209, v209, v226
	v_sub_f32_e32 v210, v210, v226
	v_sub_f32_e32 v211, v211, v226
	v_sub_f32_e32 v212, v212, v226
	v_sub_f32_e32 v213, v213, v226
	v_sub_f32_e32 v214, v214, v226
	v_sub_f32_e32 v215, v215, v226
	v_sub_f32_e32 v216, v216, v226
	v_sub_f32_e32 v217, v217, v226
	v_sub_f32_e32 v218, v218, v226
	v_sub_f32_e32 v219, v219, v226
	v_sub_f32_e32 v220, v220, v226
	v_sub_f32_e32 v221, v221, v226
	v_sub_f32_e32 v222, v222, v226
	v_sub_f32_e32 v223, v223, v226
	v_exp_f32_e32 v192, v192
	v_exp_f32_e32 v193, v193
	v_exp_f32_e32 v194, v194
	v_exp_f32_e32 v195, v195
	v_exp_f32_e32 v196, v196
	v_exp_f32_e32 v197, v197
	v_exp_f32_e32 v198, v198
	v_exp_f32_e32 v199, v199
	v_exp_f32_e32 v200, v200
	v_exp_f32_e32 v201, v201
	v_exp_f32_e32 v202, v202
	v_exp_f32_e32 v203, v203
	v_exp_f32_e32 v204, v204
	v_exp_f32_e32 v205, v205
	v_exp_f32_e32 v206, v206
	v_exp_f32_e32 v207, v207
	v_exp_f32_e32 v208, v208
	v_exp_f32_e32 v209, v209
	v_exp_f32_e32 v210, v210
	v_exp_f32_e32 v211, v211
	v_exp_f32_e32 v212, v212
	v_exp_f32_e32 v213, v213
	v_exp_f32_e32 v214, v214
	v_exp_f32_e32 v215, v215
	v_exp_f32_e32 v216, v216
	v_exp_f32_e32 v217, v217
	v_exp_f32_e32 v218, v218
	v_exp_f32_e32 v219, v219
	v_exp_f32_e32 v220, v220
	v_exp_f32_e32 v221, v221
	v_exp_f32_e32 v222, v222
	v_exp_f32_e32 v223, v223
	v_mul_f32_e32 v22, v22, v228
	v_add_f32_e32 v230, v192, v193
	v_add_f32_e32 v230, v230, v194
	v_add_f32_e32 v230, v230, v195
	v_add_f32_e32 v230, v230, v196
	v_add_f32_e32 v230, v230, v197
	v_add_f32_e32 v230, v230, v198
	v_add_f32_e32 v230, v230, v199
	v_add_f32_e32 v230, v230, v200
	v_add_f32_e32 v230, v230, v201
	v_add_f32_e32 v230, v230, v202
	v_add_f32_e32 v230, v230, v203
	v_add_f32_e32 v230, v230, v204
	v_add_f32_e32 v230, v230, v205
	v_add_f32_e32 v230, v230, v206
	v_add_f32_e32 v230, v230, v207
	v_add_f32_e32 v230, v230, v208
	v_add_f32_e32 v230, v230, v209
	v_add_f32_e32 v230, v230, v210
	v_add_f32_e32 v230, v230, v211
	v_add_f32_e32 v230, v230, v212
	v_add_f32_e32 v230, v230, v213
	v_add_f32_e32 v230, v230, v214
	v_add_f32_e32 v230, v230, v215
	v_add_f32_e32 v230, v230, v216
	v_add_f32_e32 v230, v230, v217
	v_add_f32_e32 v230, v230, v218
	v_add_f32_e32 v230, v230, v219
	v_add_f32_e32 v230, v230, v220
	v_add_f32_e32 v230, v230, v221
	v_add_f32_e32 v230, v230, v222
	v_add_f32_e32 v230, v230, v223
	v_add_f32_e32 v22, v22, v230
	v_pk_mul_f32 v[64:65], v[64:65], v[228:229] op_sel_hi:[1,0]
	v_pk_mul_f32 v[66:67], v[66:67], v[228:229] op_sel_hi:[1,0]
	v_pk_mul_f32 v[68:69], v[68:69], v[228:229] op_sel_hi:[1,0]
	v_pk_mul_f32 v[70:71], v[70:71], v[228:229] op_sel_hi:[1,0]
	v_pk_mul_f32 v[72:73], v[72:73], v[228:229] op_sel_hi:[1,0]
	v_pk_mul_f32 v[74:75], v[74:75], v[228:229] op_sel_hi:[1,0]
	v_pk_mul_f32 v[76:77], v[76:77], v[228:229] op_sel_hi:[1,0]
	v_pk_mul_f32 v[78:79], v[78:79], v[228:229] op_sel_hi:[1,0]
	v_pk_mul_f32 v[80:81], v[80:81], v[228:229] op_sel_hi:[1,0]
	v_pk_mul_f32 v[82:83], v[82:83], v[228:229] op_sel_hi:[1,0]
	v_pk_mul_f32 v[84:85], v[84:85], v[228:229] op_sel_hi:[1,0]
	v_pk_mul_f32 v[86:87], v[86:87], v[228:229] op_sel_hi:[1,0]
	v_pk_mul_f32 v[88:89], v[88:89], v[228:229] op_sel_hi:[1,0]
	v_pk_mul_f32 v[90:91], v[90:91], v[228:229] op_sel_hi:[1,0]
	v_pk_mul_f32 v[92:93], v[92:93], v[228:229] op_sel_hi:[1,0]
	v_pk_mul_f32 v[94:95], v[94:95], v[228:229] op_sel_hi:[1,0]
	v_pk_mul_f32 v[96:97], v[96:97], v[228:229] op_sel_hi:[1,0]
	v_pk_mul_f32 v[98:99], v[98:99], v[228:229] op_sel_hi:[1,0]
	v_pk_mul_f32 v[100:101], v[100:101], v[228:229] op_sel_hi:[1,0]
	v_pk_mul_f32 v[102:103], v[102:103], v[228:229] op_sel_hi:[1,0]
	v_pk_mul_f32 v[104:105], v[104:105], v[228:229] op_sel_hi:[1,0]
	v_pk_mul_f32 v[106:107], v[106:107], v[228:229] op_sel_hi:[1,0]
	v_pk_mul_f32 v[108:109], v[108:109], v[228:229] op_sel_hi:[1,0]
	v_pk_mul_f32 v[110:111], v[110:111], v[228:229] op_sel_hi:[1,0]
	v_pk_mul_f32 v[112:113], v[112:113], v[228:229] op_sel_hi:[1,0]
	v_pk_mul_f32 v[114:115], v[114:115], v[228:229] op_sel_hi:[1,0]
	v_pk_mul_f32 v[116:117], v[116:117], v[228:229] op_sel_hi:[1,0]
	v_pk_mul_f32 v[118:119], v[118:119], v[228:229] op_sel_hi:[1,0]
	v_pk_mul_f32 v[120:121], v[120:121], v[228:229] op_sel_hi:[1,0]
	v_pk_mul_f32 v[122:123], v[122:123], v[228:229] op_sel_hi:[1,0]
	v_pk_mul_f32 v[124:125], v[124:125], v[228:229] op_sel_hi:[1,0]
	v_pk_mul_f32 v[126:127], v[126:127], v[228:229] op_sel_hi:[1,0]
	v_cvt_pk_bf16_f32 v192, v192, v193
	v_cvt_pk_bf16_f32 v193, v194, v195
	v_cvt_pk_bf16_f32 v194, v196, v197
	v_cvt_pk_bf16_f32 v195, v198, v199
	v_cvt_pk_bf16_f32 v196, v200, v201
	v_cvt_pk_bf16_f32 v197, v202, v203
	v_cvt_pk_bf16_f32 v198, v204, v205
	v_cvt_pk_bf16_f32 v199, v206, v207
	v_cvt_pk_bf16_f32 v208, v208, v209
	v_cvt_pk_bf16_f32 v209, v210, v211
	v_cvt_pk_bf16_f32 v210, v212, v213
	v_cvt_pk_bf16_f32 v211, v214, v215
	v_cvt_pk_bf16_f32 v212, v216, v217
	v_cvt_pk_bf16_f32 v213, v218, v219
	v_cvt_pk_bf16_f32 v214, v220, v221
	v_cvt_pk_bf16_f32 v215, v222, v223
	s_waitcnt lgkmcnt(0)
	s_nop 0
	v_mfma_f32_32x32x16_bf16 v[64:79], a[96:99], v[192:195], v[64:79]
	v_max3_f32 v232, v32, v33, v34
	v_max3_f32 v232, v232, v35, v36
	v_max3_f32 v232, v232, v37, v38
	v_max3_f32 v232, v232, v39, v40
	v_max3_f32 v232, v232, v41, v42
	v_max3_f32 v232, v232, v43, v44
	v_max3_f32 v232, v232, v45, v46
	v_max3_f32 v232, v232, v47, v48
	v_mfma_f32_32x32x16_bf16 v[64:79], a[100:103], v[196:199], v[64:79]
	v_max3_f32 v232, v232, v49, v50
	v_max3_f32 v232, v232, v51, v52
	v_max3_f32 v232, v232, v53, v54
	v_max3_f32 v232, v232, v55, v56
	v_max3_f32 v232, v232, v57, v58
	v_max3_f32 v232, v232, v59, v60
	v_max3_f32 v232, v232, v61, v62
	v_max_f32_e32 v232, v232, v63
	v_mfma_f32_32x32x16_bf16 v[80:95], a[104:107], v[192:195], v[80:95]
	v_mov_b32_e32 v233, v232
	s_nop 1
	v_permlane32_swap_b32_e32 v232, v233
	v_max3_f32 v234, v232, v233, v21
	v_sub_f32_e32 v236, v21, v234
	v_exp_f32_e32 v236, v236
	v_mov_b32_e32 v21, v234
	v_sub_f32_e32 v32, v32, v234
	v_mfma_f32_32x32x16_bf16 v[80:95], a[108:111], v[196:199], v[80:95]
	v_sub_f32_e32 v33, v33, v234
	v_sub_f32_e32 v34, v34, v234
	v_sub_f32_e32 v35, v35, v234
	v_sub_f32_e32 v36, v36, v234
	v_sub_f32_e32 v37, v37, v234
	v_sub_f32_e32 v38, v38, v234
	v_sub_f32_e32 v39, v39, v234
	v_sub_f32_e32 v40, v40, v234
	v_mfma_f32_32x32x16_bf16 v[96:111], a[112:115], v[192:195], v[96:111]
	v_sub_f32_e32 v41, v41, v234
	v_sub_f32_e32 v42, v42, v234
	v_sub_f32_e32 v43, v43, v234
	v_sub_f32_e32 v44, v44, v234
	v_sub_f32_e32 v45, v45, v234
	v_sub_f32_e32 v46, v46, v234
	v_sub_f32_e32 v47, v47, v234
	v_sub_f32_e32 v48, v48, v234
	v_mfma_f32_32x32x16_bf16 v[96:111], a[116:119], v[196:199], v[96:111]
	v_sub_f32_e32 v49, v49, v234
	v_sub_f32_e32 v50, v50, v234
	v_sub_f32_e32 v51, v51, v234
	v_sub_f32_e32 v52, v52, v234
	v_sub_f32_e32 v53, v53, v234
	v_sub_f32_e32 v54, v54, v234
	v_sub_f32_e32 v55, v55, v234
	v_sub_f32_e32 v56, v56, v234
	v_mfma_f32_32x32x16_bf16 v[112:127], a[120:123], v[192:195], v[112:127]
	v_sub_f32_e32 v57, v57, v234
	v_sub_f32_e32 v58, v58, v234
	v_sub_f32_e32 v59, v59, v234
	v_sub_f32_e32 v60, v60, v234
	v_sub_f32_e32 v61, v61, v234
	v_sub_f32_e32 v62, v62, v234
	v_sub_f32_e32 v63, v63, v234
	v_exp_f32_e32 v32, v32
	v_mfma_f32_32x32x16_bf16 v[112:127], a[124:127], v[196:199], v[112:127]
	v_exp_f32_e32 v33, v33
	v_exp_f32_e32 v34, v34
	v_exp_f32_e32 v35, v35
	v_exp_f32_e32 v36, v36
	v_exp_f32_e32 v37, v37
	v_exp_f32_e32 v38, v38
	v_exp_f32_e32 v39, v39
	v_exp_f32_e32 v40, v40
	v_mfma_f32_32x32x16_bf16 v[64:79], a[128:131], v[208:211], v[64:79]
	v_exp_f32_e32 v41, v41
	v_exp_f32_e32 v42, v42
	v_exp_f32_e32 v43, v43
	v_exp_f32_e32 v44, v44
	v_exp_f32_e32 v45, v45
	v_exp_f32_e32 v46, v46
	v_exp_f32_e32 v47, v47
	v_exp_f32_e32 v48, v48
	v_mfma_f32_32x32x16_bf16 v[64:79], a[132:135], v[212:215], v[64:79]
	v_exp_f32_e32 v49, v49
	v_exp_f32_e32 v50, v50
	v_exp_f32_e32 v51, v51
	v_exp_f32_e32 v52, v52
	v_exp_f32_e32 v53, v53
	v_exp_f32_e32 v54, v54
	v_exp_f32_e32 v55, v55
	v_exp_f32_e32 v56, v56
	v_mfma_f32_32x32x16_bf16 v[80:95], a[136:139], v[208:211], v[80:95]
	v_exp_f32_e32 v57, v57
	v_exp_f32_e32 v58, v58
	v_exp_f32_e32 v59, v59
	v_exp_f32_e32 v60, v60
	v_exp_f32_e32 v61, v61
	v_exp_f32_e32 v62, v62
	v_exp_f32_e32 v63, v63
	v_mul_f32_e32 v23, v23, v236
	v_mfma_f32_32x32x16_bf16 v[80:95], a[140:143], v[212:215], v[80:95]
	v_add_f32_e32 v238, v32, v33
	v_add_f32_e32 v238, v238, v34
	v_add_f32_e32 v238, v238, v35
	v_add_f32_e32 v238, v238, v36
	v_add_f32_e32 v238, v238, v37
	v_add_f32_e32 v238, v238, v38
	v_add_f32_e32 v238, v238, v39
	v_add_f32_e32 v238, v238, v40
	v_mfma_f32_32x32x16_bf16 v[96:111], a[144:147], v[208:211], v[96:111]
	v_add_f32_e32 v238, v238, v41
	v_add_f32_e32 v238, v238, v42
	v_add_f32_e32 v238, v238, v43
	v_add_f32_e32 v238, v238, v44
	v_add_f32_e32 v238, v238, v45
	v_add_f32_e32 v238, v238, v46
	v_add_f32_e32 v238, v238, v47
	v_add_f32_e32 v238, v238, v48
	v_mfma_f32_32x32x16_bf16 v[96:111], a[148:151], v[212:215], v[96:111]
	v_add_f32_e32 v238, v238, v49
	v_add_f32_e32 v238, v238, v50
	v_add_f32_e32 v238, v238, v51
	v_add_f32_e32 v238, v238, v52
	v_add_f32_e32 v238, v238, v53
	v_add_f32_e32 v238, v238, v54
	v_add_f32_e32 v238, v238, v55
	v_add_f32_e32 v238, v238, v56
	v_mfma_f32_32x32x16_bf16 v[112:127], a[152:155], v[208:211], v[112:127]
	v_add_f32_e32 v238, v238, v57
	v_add_f32_e32 v238, v238, v58
	v_add_f32_e32 v238, v238, v59
	v_add_f32_e32 v238, v238, v60
	v_add_f32_e32 v238, v238, v61
	v_add_f32_e32 v238, v238, v62
	v_add_f32_e32 v238, v238, v63
	v_add_f32_e32 v23, v23, v238
	v_mfma_f32_32x32x16_bf16 v[112:127], a[156:159], v[212:215], v[112:127]
	v_pk_mul_f32 v[128:129], v[128:129], v[236:237] op_sel_hi:[1,0]
	v_pk_mul_f32 v[130:131], v[130:131], v[236:237] op_sel_hi:[1,0]
	v_pk_mul_f32 v[132:133], v[132:133], v[236:237] op_sel_hi:[1,0]
	v_pk_mul_f32 v[134:135], v[134:135], v[236:237] op_sel_hi:[1,0]
	v_pk_mul_f32 v[136:137], v[136:137], v[236:237] op_sel_hi:[1,0]
	v_pk_mul_f32 v[138:139], v[138:139], v[236:237] op_sel_hi:[1,0]
	v_pk_mul_f32 v[140:141], v[140:141], v[236:237] op_sel_hi:[1,0]
	v_pk_mul_f32 v[142:143], v[142:143], v[236:237] op_sel_hi:[1,0]
	v_pk_mul_f32 v[144:145], v[144:145], v[236:237] op_sel_hi:[1,0]
	v_pk_mul_f32 v[146:147], v[146:147], v[236:237] op_sel_hi:[1,0]
	v_pk_mul_f32 v[148:149], v[148:149], v[236:237] op_sel_hi:[1,0]
	v_pk_mul_f32 v[150:151], v[150:151], v[236:237] op_sel_hi:[1,0]
	v_pk_mul_f32 v[152:153], v[152:153], v[236:237] op_sel_hi:[1,0]
	v_pk_mul_f32 v[154:155], v[154:155], v[236:237] op_sel_hi:[1,0]
	v_pk_mul_f32 v[156:157], v[156:157], v[236:237] op_sel_hi:[1,0]
	v_pk_mul_f32 v[158:159], v[158:159], v[236:237] op_sel_hi:[1,0]
	v_pk_mul_f32 v[160:161], v[160:161], v[236:237] op_sel_hi:[1,0]
	v_pk_mul_f32 v[162:163], v[162:163], v[236:237] op_sel_hi:[1,0]
	v_pk_mul_f32 v[164:165], v[164:165], v[236:237] op_sel_hi:[1,0]
	v_pk_mul_f32 v[166:167], v[166:167], v[236:237] op_sel_hi:[1,0]
	v_pk_mul_f32 v[168:169], v[168:169], v[236:237] op_sel_hi:[1,0]
	v_pk_mul_f32 v[170:171], v[170:171], v[236:237] op_sel_hi:[1,0]
	v_pk_mul_f32 v[172:173], v[172:173], v[236:237] op_sel_hi:[1,0]
	v_pk_mul_f32 v[174:175], v[174:175], v[236:237] op_sel_hi:[1,0]
	v_pk_mul_f32 v[176:177], v[176:177], v[236:237] op_sel_hi:[1,0]
	v_pk_mul_f32 v[178:179], v[178:179], v[236:237] op_sel_hi:[1,0]
	v_pk_mul_f32 v[180:181], v[180:181], v[236:237] op_sel_hi:[1,0]
	v_pk_mul_f32 v[182:183], v[182:183], v[236:237] op_sel_hi:[1,0]
	v_pk_mul_f32 v[184:185], v[184:185], v[236:237] op_sel_hi:[1,0]
	v_pk_mul_f32 v[186:187], v[186:187], v[236:237] op_sel_hi:[1,0]
	v_pk_mul_f32 v[188:189], v[188:189], v[236:237] op_sel_hi:[1,0]
	v_pk_mul_f32 v[190:191], v[190:191], v[236:237] op_sel_hi:[1,0]
	v_cvt_pk_bf16_f32 v32, v32, v33
	v_cvt_pk_bf16_f32 v33, v34, v35
	v_cvt_pk_bf16_f32 v34, v36, v37
	v_cvt_pk_bf16_f32 v35, v38, v39
	v_cvt_pk_bf16_f32 v36, v40, v41
	v_cvt_pk_bf16_f32 v37, v42, v43
	v_cvt_pk_bf16_f32 v38, v44, v45
	v_cvt_pk_bf16_f32 v39, v46, v47
	v_cvt_pk_bf16_f32 v48, v48, v49
	v_cvt_pk_bf16_f32 v49, v50, v51
	v_cvt_pk_bf16_f32 v50, v52, v53
	v_cvt_pk_bf16_f32 v51, v54, v55
	v_cvt_pk_bf16_f32 v52, v56, v57
	v_cvt_pk_bf16_f32 v53, v58, v59
	v_cvt_pk_bf16_f32 v54, v60, v61
	v_cvt_pk_bf16_f32 v55, v62, v63
	s_nop 1
	v_mfma_f32_32x32x16_bf16 v[128:143], a[96:99], v[32:35], v[128:143]
	v_mfma_f32_32x32x16_bf16 v[128:143], a[100:103], v[36:39], v[128:143]
	v_mfma_f32_32x32x16_bf16 v[144:159], a[104:107], v[32:35], v[144:159]
	v_mfma_f32_32x32x16_bf16 v[144:159], a[108:111], v[36:39], v[144:159]
	v_mfma_f32_32x32x16_bf16 v[160:175], a[112:115], v[32:35], v[160:175]
	v_mfma_f32_32x32x16_bf16 v[160:175], a[116:119], v[36:39], v[160:175]
	v_mfma_f32_32x32x16_bf16 v[176:191], a[120:123], v[32:35], v[176:191]
	v_mfma_f32_32x32x16_bf16 v[176:191], a[124:127], v[36:39], v[176:191]
	v_mfma_f32_32x32x16_bf16 v[128:143], a[128:131], v[48:51], v[128:143]
	v_mfma_f32_32x32x16_bf16 v[128:143], a[132:135], v[52:55], v[128:143]
	v_mfma_f32_32x32x16_bf16 v[144:159], a[136:139], v[48:51], v[144:159]
	v_mfma_f32_32x32x16_bf16 v[144:159], a[140:143], v[52:55], v[144:159]
	v_mfma_f32_32x32x16_bf16 v[160:175], a[144:147], v[48:51], v[160:175]
	v_mfma_f32_32x32x16_bf16 v[160:175], a[148:151], v[52:55], v[160:175]
	v_mfma_f32_32x32x16_bf16 v[176:191], a[152:155], v[48:51], v[176:191]
	v_mfma_f32_32x32x16_bf16 v[176:191], a[156:159], v[52:55], v[176:191]
	s_branch .Lat_skip
.Lat_diag:
	s_waitcnt lgkmcnt(15)
	v_mfma_f32_32x32x16_bf16 v[192:207], a[32:35], a[0:3], 0
	s_waitcnt lgkmcnt(11)
	v_mfma_f32_32x32x16_bf16 v[208:223], a[48:51], a[0:3], 0
	s_waitcnt lgkmcnt(14)
	v_mfma_f32_32x32x16_bf16 v[192:207], a[36:39], a[4:7], v[192:207]
	s_waitcnt lgkmcnt(10)
	v_mfma_f32_32x32x16_bf16 v[208:223], a[52:55], a[4:7], v[208:223]
	s_waitcnt lgkmcnt(13)
	v_mfma_f32_32x32x16_bf16 v[192:207], a[40:43], a[8:11], v[192:207]
	s_waitcnt lgkmcnt(9)
	v_mfma_f32_32x32x16_bf16 v[208:223], a[56:59], a[8:11], v[208:223]
	s_waitcnt lgkmcnt(12)
	v_mfma_f32_32x32x16_bf16 v[192:207], a[44:47], a[12:15], v[192:207]
	s_waitcnt lgkmcnt(8)
	v_mfma_f32_32x32x16_bf16 v[208:223], a[60:63], a[12:15], v[208:223]
	s_waitcnt lgkmcnt(7)
	v_mfma_f32_32x32x16_bf16 v[32:47], a[64:67], a[16:19], 0
	s_waitcnt lgkmcnt(3)
	v_mfma_f32_32x32x16_bf16 v[48:63], a[80:83], a[16:19], 0
	s_waitcnt lgkmcnt(6)
	v_mfma_f32_32x32x16_bf16 v[32:47], a[68:71], a[20:23], v[32:47]
	s_waitcnt lgkmcnt(2)
	v_mfma_f32_32x32x16_bf16 v[48:63], a[84:87], a[20:23], v[48:63]
	ds_read2_b64 a[96:99], v7 offset0:0 offset1:2
	ds_read2_b64 a[100:103], v7 offset0:4 offset1:6
	ds_read2_b64 a[128:131], v7 offset0:8 offset1:10
	ds_read2_b64 a[132:135], v7 offset0:12 offset1:14
	v_add_u32_e32 v28, 0x1200, v7
	ds_read2_b64 a[104:107], v28 offset0:0 offset1:2
	ds_read2_b64 a[108:111], v28 offset0:4 offset1:6
	ds_read2_b64 a[136:139], v28 offset0:8 offset1:10
	ds_read2_b64 a[140:143], v28 offset0:12 offset1:14
	v_add_u32_e32 v28, 0x2400, v7
	ds_read2_b64 a[112:115], v28 offset0:0 offset1:2
	ds_read2_b64 a[116:119], v28 offset0:4 offset1:6
	ds_read2_b64 a[144:147], v28 offset0:8 offset1:10
	ds_read2_b64 a[148:151], v28 offset0:12 offset1:14
	v_add_u32_e32 v28, 0x3600, v7
	ds_read2_b64 a[120:123], v28 offset0:0 offset1:2
	ds_read2_b64 a[124:127], v28 offset0:4 offset1:6
	ds_read2_b64 a[152:155], v28 offset0:8 offset1:10
	ds_read2_b64 a[156:159], v28 offset0:12 offset1:14
	s_waitcnt lgkmcnt(15)
	v_mfma_f32_32x32x16_bf16 v[32:47], a[72:75], a[24:27], v[32:47]
	v_cmp_gt_i32_e64 s[0:1], 0, v25
	v_cmp_gt_i32_e64 s[4:5], 1, v25
	v_cmp_gt_i32_e64 s[10:11], 2, v25
	v_cmp_gt_i32_e64 s[20:21], 3, v25
	v_cndmask_b32_e64 v192, v192, v27, s[0:1]
	v_cndmask_b32_e64 v193, v193, v27, s[4:5]
	v_cndmask_b32_e64 v194, v194, v27, s[10:11]
	v_cndmask_b32_e64 v195, v195, v27, s[20:21]
	s_waitcnt lgkmcnt(15)
	v_mfma_f32_32x32x16_bf16 v[48:63], a[88:91], a[24:27], v[48:63]
	v_cmp_gt_i32_e64 s[0:1], 8, v25
	v_cmp_gt_i32_e64 s[4:5], 9, v25
	v_cmp_gt_i32_e64 s[10:11], 10, v25
	v_cmp_gt_i32_e64 s[20:21], 11, v25
	v_cndmask_b32_e64 v196, v196, v27, s[0:1]
	v_cndmask_b32_e64 v197, v197, v27, s[4:5]
	v_cndmask_b32_e64 v198, v198, v27, s[10:11]
	v_cndmask_b32_e64 v199, v199, v27, s[20:21]
	s_waitcnt lgkmcnt(15)
	v_mfma_f32_32x32x16_bf16 v[32:47], a[76:79], a[28:31], v[32:47]
	v_cmp_gt_i32_e64 s[0:1], 16, v25
	v_cmp_gt_i32_e64 s[4:5], 17, v25
	v_cmp_gt_i32_e64 s[10:11], 18, v25
	v_cmp_gt_i32_e64 s[20:21], 19, v25
	v_cndmask_b32_e64 v200, v200, v27, s[0:1]
	v_cndmask_b32_e64 v201, v201, v27, s[4:5]
	v_cndmask_b32_e64 v202, v202, v27, s[10:11]
	v_cndmask_b32_e64 v203, v203, v27, s[20:21]
	s_waitcnt lgkmcnt(15)
	v_mfma_f32_32x32x16_bf16 v[48:63], a[92:95], a[28:31], v[48:63]
	v_cmp_gt_i32_e64 s[0:1], 24, v25
	v_cmp_gt_i32_e64 s[4:5], 25, v25
	v_cmp_gt_i32_e64 s[10:11], 26, v25
	v_cmp_gt_i32_e64 s[20:21], 27, v25
	v_cndmask_b32_e64 v204, v204, v27, s[0:1]
	v_cndmask_b32_e64 v205, v205, v27, s[4:5]
	v_cndmask_b32_e64 v206, v206, v27, s[10:11]
	v_cndmask_b32_e64 v207, v207, v27, s[20:21]
	v_cmp_gt_i32_e64 s[0:1], 32, v25
	v_cmp_gt_i32_e64 s[4:5], 33, v25
	v_cmp_gt_i32_e64 s[10:11], 34, v25
	v_cmp_gt_i32_e64 s[20:21], 35, v25
	v_cndmask_b32_e64 v208, v208, v27, s[0:1]
	v_cndmask_b32_e64 v209, v209, v27, s[4:5]
	v_cndmask_b32_e64 v210, v210, v27, s[10:11]
	v_cndmask_b32_e64 v211, v211, v27, s[20:21]
	v_cmp_gt_i32_e64 s[0:1], 40, v25
	v_cmp_gt_i32_e64 s[4:5], 41, v25
	v_cmp_gt_i32_e64 s[10:11], 42, v25
	v_cmp_gt_i32_e64 s[20:21], 43, v25
	v_cndmask_b32_e64 v212, v212, v27, s[0:1]
	v_cndmask_b32_e64 v213, v213, v27, s[4:5]
	v_cndmask_b32_e64 v214, v214, v27, s[10:11]
	v_cndmask_b32_e64 v215, v215, v27, s[20:21]
	v_cmp_gt_i32_e64 s[0:1], 48, v25
	v_cmp_gt_i32_e64 s[4:5], 49, v25
	v_cmp_gt_i32_e64 s[10:11], 50, v25
	v_cmp_gt_i32_e64 s[20:21], 51, v25
	v_cndmask_b32_e64 v216, v216, v27, s[0:1]
	v_cndmask_b32_e64 v217, v217, v27, s[4:5]
	v_cndmask_b32_e64 v218, v218, v27, s[10:11]
	v_cndmask_b32_e64 v219, v219, v27, s[20:21]
	v_cmp_gt_i32_e64 s[0:1], 56, v25
	v_cmp_gt_i32_e64 s[4:5], 57, v25
	v_cmp_gt_i32_e64 s[10:11], 58, v25
	v_cmp_gt_i32_e64 s[20:21], 59, v25
	v_cndmask_b32_e64 v220, v220, v27, s[0:1]
	v_cndmask_b32_e64 v221, v221, v27, s[4:5]
	v_cndmask_b32_e64 v222, v222, v27, s[10:11]
	v_cndmask_b32_e64 v223, v223, v27, s[20:21]
	v_max3_f32 v224, v192, v193, v194
	v_max3_f32 v224, v224, v195, v196
	v_max3_f32 v224, v224, v197, v198
	v_max3_f32 v224, v224, v199, v200
	v_max3_f32 v224, v224, v201, v202
	v_max3_f32 v224, v224, v203, v204
	v_max3_f32 v224, v224, v205, v206
	v_max3_f32 v224, v224, v207, v208
	v_max3_f32 v224, v224, v209, v210
	v_max3_f32 v224, v224, v211, v212
	v_max3_f32 v224, v224, v213, v214
	v_max3_f32 v224, v224, v215, v216
	v_max3_f32 v224, v224, v217, v218
	v_max3_f32 v224, v224, v219, v220
	v_max3_f32 v224, v224, v221, v222
	v_max_f32_e32 v224, v224, v223
	v_mov_b32_e32 v225, v224
	s_nop 1
	v_permlane32_swap_b32_e32 v224, v225
	v_max3_f32 v226, v224, v225, v20
	v_sub_f32_e32 v228, v20, v226
	v_exp_f32_e32 v228, v228
	v_mov_b32_e32 v20, v226
	v_sub_f32_e32 v192, v192, v226
	v_sub_f32_e32 v193, v193, v226
	v_sub_f32_e32 v194, v194, v226
	v_sub_f32_e32 v195, v195, v226
	v_sub_f32_e32 v196, v196, v226
	v_sub_f32_e32 v197, v197, v226
	v_sub_f32_e32 v198, v198, v226
	v_sub_f32_e32 v199, v199, v226
	v_sub_f32_e32 v200, v200, v226
	v_sub_f32_e32 v201, v201, v226
	v_sub_f32_e32 v202, v202, v226
	v_sub_f32_e32 v203, v203, v226
	v_sub_f32_e32 v204, v204, v226
	v_sub_f32_e32 v205, v205, v226
	v_sub_f32_e32 v206, v206, v226
	v_sub_f32_e32 v207, v207, v226
	v_sub_f32_e32 v208, v208, v226
	v_sub_f32_e32 v209, v209, v226
	v_sub_f32_e32 v210, v210, v226
	v_sub_f32_e32 v211, v211, v226
	v_sub_f32_e32 v212, v212, v226
	v_sub_f32_e32 v213, v213, v226
	v_sub_f32_e32 v214, v214, v226
	v_sub_f32_e32 v215, v215, v226
	v_sub_f32_e32 v216, v216, v226
	v_sub_f32_e32 v217, v217, v226
	v_sub_f32_e32 v218, v218, v226
	v_sub_f32_e32 v219, v219, v226
	v_sub_f32_e32 v220, v220, v226
	v_sub_f32_e32 v221, v221, v226
	v_sub_f32_e32 v222, v222, v226
	v_sub_f32_e32 v223, v223, v226
	v_exp_f32_e32 v192, v192
	v_exp_f32_e32 v193, v193
	v_exp_f32_e32 v194, v194
	v_exp_f32_e32 v195, v195
	v_exp_f32_e32 v196, v196
	v_exp_f32_e32 v197, v197
	v_exp_f32_e32 v198, v198
	v_exp_f32_e32 v199, v199
	v_exp_f32_e32 v200, v200
	v_exp_f32_e32 v201, v201
	v_exp_f32_e32 v202, v202
	v_exp_f32_e32 v203, v203
	v_exp_f32_e32 v204, v204
	v_exp_f32_e32 v205, v205
	v_exp_f32_e32 v206, v206
	v_exp_f32_e32 v207, v207
	v_exp_f32_e32 v208, v208
	v_exp_f32_e32 v209, v209
	v_exp_f32_e32 v210, v210
	v_exp_f32_e32 v211, v211
	v_exp_f32_e32 v212, v212
	v_exp_f32_e32 v213, v213
	v_exp_f32_e32 v214, v214
	v_exp_f32_e32 v215, v215
	v_exp_f32_e32 v216, v216
	v_exp_f32_e32 v217, v217
	v_exp_f32_e32 v218, v218
	v_exp_f32_e32 v219, v219
	v_exp_f32_e32 v220, v220
	v_exp_f32_e32 v221, v221
	v_exp_f32_e32 v222, v222
	v_exp_f32_e32 v223, v223
	v_mul_f32_e32 v22, v22, v228
	v_add_f32_e32 v230, v192, v193
	v_add_f32_e32 v230, v230, v194
	v_add_f32_e32 v230, v230, v195
	v_add_f32_e32 v230, v230, v196
	v_add_f32_e32 v230, v230, v197
	v_add_f32_e32 v230, v230, v198
	v_add_f32_e32 v230, v230, v199
	v_add_f32_e32 v230, v230, v200
	v_add_f32_e32 v230, v230, v201
	v_add_f32_e32 v230, v230, v202
	v_add_f32_e32 v230, v230, v203
	v_add_f32_e32 v230, v230, v204
	v_add_f32_e32 v230, v230, v205
	v_add_f32_e32 v230, v230, v206
	v_add_f32_e32 v230, v230, v207
	v_add_f32_e32 v230, v230, v208
	v_add_f32_e32 v230, v230, v209
	v_add_f32_e32 v230, v230, v210
	v_add_f32_e32 v230, v230, v211
	v_add_f32_e32 v230, v230, v212
	v_add_f32_e32 v230, v230, v213
	v_add_f32_e32 v230, v230, v214
	v_add_f32_e32 v230, v230, v215
	v_add_f32_e32 v230, v230, v216
	v_add_f32_e32 v230, v230, v217
	v_add_f32_e32 v230, v230, v218
	v_add_f32_e32 v230, v230, v219
	v_add_f32_e32 v230, v230, v220
	v_add_f32_e32 v230, v230, v221
	v_add_f32_e32 v230, v230, v222
	v_add_f32_e32 v230, v230, v223
	v_add_f32_e32 v22, v22, v230
	v_pk_mul_f32 v[64:65], v[64:65], v[228:229] op_sel_hi:[1,0]
	v_pk_mul_f32 v[66:67], v[66:67], v[228:229] op_sel_hi:[1,0]
	v_pk_mul_f32 v[68:69], v[68:69], v[228:229] op_sel_hi:[1,0]
	v_pk_mul_f32 v[70:71], v[70:71], v[228:229] op_sel_hi:[1,0]
	v_pk_mul_f32 v[72:73], v[72:73], v[228:229] op_sel_hi:[1,0]
	v_pk_mul_f32 v[74:75], v[74:75], v[228:229] op_sel_hi:[1,0]
	v_pk_mul_f32 v[76:77], v[76:77], v[228:229] op_sel_hi:[1,0]
	v_pk_mul_f32 v[78:79], v[78:79], v[228:229] op_sel_hi:[1,0]
	v_pk_mul_f32 v[80:81], v[80:81], v[228:229] op_sel_hi:[1,0]
	v_pk_mul_f32 v[82:83], v[82:83], v[228:229] op_sel_hi:[1,0]
	v_pk_mul_f32 v[84:85], v[84:85], v[228:229] op_sel_hi:[1,0]
	v_pk_mul_f32 v[86:87], v[86:87], v[228:229] op_sel_hi:[1,0]
	v_pk_mul_f32 v[88:89], v[88:89], v[228:229] op_sel_hi:[1,0]
	v_pk_mul_f32 v[90:91], v[90:91], v[228:229] op_sel_hi:[1,0]
	v_pk_mul_f32 v[92:93], v[92:93], v[228:229] op_sel_hi:[1,0]
	v_pk_mul_f32 v[94:95], v[94:95], v[228:229] op_sel_hi:[1,0]
	v_pk_mul_f32 v[96:97], v[96:97], v[228:229] op_sel_hi:[1,0]
	v_pk_mul_f32 v[98:99], v[98:99], v[228:229] op_sel_hi:[1,0]
	v_pk_mul_f32 v[100:101], v[100:101], v[228:229] op_sel_hi:[1,0]
	v_pk_mul_f32 v[102:103], v[102:103], v[228:229] op_sel_hi:[1,0]
	v_pk_mul_f32 v[104:105], v[104:105], v[228:229] op_sel_hi:[1,0]
	v_pk_mul_f32 v[106:107], v[106:107], v[228:229] op_sel_hi:[1,0]
	v_pk_mul_f32 v[108:109], v[108:109], v[228:229] op_sel_hi:[1,0]
	v_pk_mul_f32 v[110:111], v[110:111], v[228:229] op_sel_hi:[1,0]
	v_pk_mul_f32 v[112:113], v[112:113], v[228:229] op_sel_hi:[1,0]
	v_pk_mul_f32 v[114:115], v[114:115], v[228:229] op_sel_hi:[1,0]
	v_pk_mul_f32 v[116:117], v[116:117], v[228:229] op_sel_hi:[1,0]
	v_pk_mul_f32 v[118:119], v[118:119], v[228:229] op_sel_hi:[1,0]
	v_pk_mul_f32 v[120:121], v[120:121], v[228:229] op_sel_hi:[1,0]
	v_pk_mul_f32 v[122:123], v[122:123], v[228:229] op_sel_hi:[1,0]
	v_pk_mul_f32 v[124:125], v[124:125], v[228:229] op_sel_hi:[1,0]
	v_pk_mul_f32 v[126:127], v[126:127], v[228:229] op_sel_hi:[1,0]
	v_cvt_pk_bf16_f32 v192, v192, v193
	v_cvt_pk_bf16_f32 v193, v194, v195
	v_cvt_pk_bf16_f32 v194, v196, v197
	v_cvt_pk_bf16_f32 v195, v198, v199
	v_cvt_pk_bf16_f32 v196, v200, v201
	v_cvt_pk_bf16_f32 v197, v202, v203
	v_cvt_pk_bf16_f32 v198, v204, v205
	v_cvt_pk_bf16_f32 v199, v206, v207
	v_cvt_pk_bf16_f32 v208, v208, v209
	v_cvt_pk_bf16_f32 v209, v210, v211
	v_cvt_pk_bf16_f32 v210, v212, v213
	v_cvt_pk_bf16_f32 v211, v214, v215
	v_cvt_pk_bf16_f32 v212, v216, v217
	v_cvt_pk_bf16_f32 v213, v218, v219
	v_cvt_pk_bf16_f32 v214, v220, v221
	v_cvt_pk_bf16_f32 v215, v222, v223
	s_waitcnt lgkmcnt(0)
	s_nop 0
	v_mfma_f32_32x32x16_bf16 v[64:79], a[96:99], v[192:195], v[64:79]
	v_cmp_gt_i32_e64 s[0:1], 0, v25
	v_cmp_gt_i32_e64 s[4:5], 1, v25
	v_cmp_gt_i32_e64 s[10:11], 2, v25
	v_cmp_gt_i32_e64 s[20:21], 3, v25
	v_cndmask_b32_e64 v32, v32, v27, s[0:1]
	v_cndmask_b32_e64 v33, v33, v27, s[4:5]
	v_cndmask_b32_e64 v34, v34, v27, s[10:11]
	v_cndmask_b32_e64 v35, v35, v27, s[20:21]
	v_mfma_f32_32x32x16_bf16 v[64:79], a[100:103], v[196:199], v[64:79]
	v_cmp_gt_i32_e64 s[0:1], 8, v25
	v_cmp_gt_i32_e64 s[4:5], 9, v25
	v_cmp_gt_i32_e64 s[10:11], 10, v25
	v_cmp_gt_i32_e64 s[20:21], 11, v25
	v_cndmask_b32_e64 v36, v36, v27, s[0:1]
	v_cndmask_b32_e64 v37, v37, v27, s[4:5]
	v_cndmask_b32_e64 v38, v38, v27, s[10:11]
	v_cndmask_b32_e64 v39, v39, v27, s[20:21]
	v_mfma_f32_32x32x16_bf16 v[80:95], a[104:107], v[192:195], v[80:95]
	v_cmp_gt_i32_e64 s[0:1], 16, v25
	v_cmp_gt_i32_e64 s[4:5], 17, v25
	v_cmp_gt_i32_e64 s[10:11], 18, v25
	v_cmp_gt_i32_e64 s[20:21], 19, v25
	v_cndmask_b32_e64 v40, v40, v27, s[0:1]
	v_cndmask_b32_e64 v41, v41, v27, s[4:5]
	v_cndmask_b32_e64 v42, v42, v27, s[10:11]
	v_cndmask_b32_e64 v43, v43, v27, s[20:21]
	v_mfma_f32_32x32x16_bf16 v[80:95], a[108:111], v[196:199], v[80:95]
	v_cmp_gt_i32_e64 s[0:1], 24, v25
	v_cmp_gt_i32_e64 s[4:5], 25, v25
	v_cmp_gt_i32_e64 s[10:11], 26, v25
	v_cmp_gt_i32_e64 s[20:21], 27, v25
	v_cndmask_b32_e64 v44, v44, v27, s[0:1]
	v_cndmask_b32_e64 v45, v45, v27, s[4:5]
	v_cndmask_b32_e64 v46, v46, v27, s[10:11]
	v_cndmask_b32_e64 v47, v47, v27, s[20:21]
	v_mfma_f32_32x32x16_bf16 v[96:111], a[112:115], v[192:195], v[96:111]
	v_cmp_gt_i32_e64 s[0:1], 32, v25
	v_cmp_gt_i32_e64 s[4:5], 33, v25
	v_cmp_gt_i32_e64 s[10:11], 34, v25
	v_cmp_gt_i32_e64 s[20:21], 35, v25
	v_cndmask_b32_e64 v48, v48, v27, s[0:1]
	v_cndmask_b32_e64 v49, v49, v27, s[4:5]
	v_cndmask_b32_e64 v50, v50, v27, s[10:11]
	v_cndmask_b32_e64 v51, v51, v27, s[20:21]
	v_mfma_f32_32x32x16_bf16 v[96:111], a[116:119], v[196:199], v[96:111]
	v_cmp_gt_i32_e64 s[0:1], 40, v25
	v_cmp_gt_i32_e64 s[4:5], 41, v25
	v_cmp_gt_i32_e64 s[10:11], 42, v25
	v_cmp_gt_i32_e64 s[20:21], 43, v25
	v_cndmask_b32_e64 v52, v52, v27, s[0:1]
	v_cndmask_b32_e64 v53, v53, v27, s[4:5]
	v_cndmask_b32_e64 v54, v54, v27, s[10:11]
	v_cndmask_b32_e64 v55, v55, v27, s[20:21]
	v_mfma_f32_32x32x16_bf16 v[112:127], a[120:123], v[192:195], v[112:127]
	v_cmp_gt_i32_e64 s[0:1], 48, v25
	v_cmp_gt_i32_e64 s[4:5], 49, v25
	v_cmp_gt_i32_e64 s[10:11], 50, v25
	v_cmp_gt_i32_e64 s[20:21], 51, v25
	v_cndmask_b32_e64 v56, v56, v27, s[0:1]
	v_cndmask_b32_e64 v57, v57, v27, s[4:5]
	v_cndmask_b32_e64 v58, v58, v27, s[10:11]
	v_cndmask_b32_e64 v59, v59, v27, s[20:21]
	v_mfma_f32_32x32x16_bf16 v[112:127], a[124:127], v[196:199], v[112:127]
	v_cmp_gt_i32_e64 s[0:1], 56, v25
	v_cmp_gt_i32_e64 s[4:5], 57, v25
	v_cmp_gt_i32_e64 s[10:11], 58, v25
	v_cmp_gt_i32_e64 s[20:21], 59, v25
	v_cndmask_b32_e64 v60, v60, v27, s[0:1]
	v_cndmask_b32_e64 v61, v61, v27, s[4:5]
	v_cndmask_b32_e64 v62, v62, v27, s[10:11]
	v_cndmask_b32_e64 v63, v63, v27, s[20:21]
	v_mfma_f32_32x32x16_bf16 v[64:79], a[128:131], v[208:211], v[64:79]
	v_max3_f32 v232, v32, v33, v34
	v_max3_f32 v232, v232, v35, v36
	v_max3_f32 v232, v232, v37, v38
	v_max3_f32 v232, v232, v39, v40
	v_max3_f32 v232, v232, v41, v42
	v_max3_f32 v232, v232, v43, v44
	v_max3_f32 v232, v232, v45, v46
	v_max3_f32 v232, v232, v47, v48
	v_mfma_f32_32x32x16_bf16 v[64:79], a[132:135], v[212:215], v[64:79]
	v_max3_f32 v232, v232, v49, v50
	v_max3_f32 v232, v232, v51, v52
	v_max3_f32 v232, v232, v53, v54
	v_max3_f32 v232, v232, v55, v56
	v_max3_f32 v232, v232, v57, v58
	v_max3_f32 v232, v232, v59, v60
	v_max3_f32 v232, v232, v61, v62
	v_max_f32_e32 v232, v232, v63
	v_mfma_f32_32x32x16_bf16 v[80:95], a[136:139], v[208:211], v[80:95]
	v_mov_b32_e32 v233, v232
	s_nop 1
	v_permlane32_swap_b32_e32 v232, v233
	v_max3_f32 v234, v232, v233, v21
	v_sub_f32_e32 v236, v21, v234
	v_exp_f32_e32 v236, v236
	v_mov_b32_e32 v21, v234
	v_sub_f32_e32 v32, v32, v234
	v_mfma_f32_32x32x16_bf16 v[80:95], a[140:143], v[212:215], v[80:95]
	v_sub_f32_e32 v33, v33, v234
	v_sub_f32_e32 v34, v34, v234
	v_sub_f32_e32 v35, v35, v234
	v_sub_f32_e32 v36, v36, v234
	v_sub_f32_e32 v37, v37, v234
	v_sub_f32_e32 v38, v38, v234
	v_sub_f32_e32 v39, v39, v234
	v_sub_f32_e32 v40, v40, v234
	v_mfma_f32_32x32x16_bf16 v[96:111], a[144:147], v[208:211], v[96:111]
	v_sub_f32_e32 v41, v41, v234
	v_sub_f32_e32 v42, v42, v234
	v_sub_f32_e32 v43, v43, v234
	v_sub_f32_e32 v44, v44, v234
	v_sub_f32_e32 v45, v45, v234
	v_sub_f32_e32 v46, v46, v234
	v_sub_f32_e32 v47, v47, v234
	v_sub_f32_e32 v48, v48, v234
	v_mfma_f32_32x32x16_bf16 v[96:111], a[148:151], v[212:215], v[96:111]
	v_sub_f32_e32 v49, v49, v234
	v_sub_f32_e32 v50, v50, v234
	v_sub_f32_e32 v51, v51, v234
	v_sub_f32_e32 v52, v52, v234
	v_sub_f32_e32 v53, v53, v234
	v_sub_f32_e32 v54, v54, v234
	v_sub_f32_e32 v55, v55, v234
	v_sub_f32_e32 v56, v56, v234
	v_mfma_f32_32x32x16_bf16 v[112:127], a[152:155], v[208:211], v[112:127]
	v_sub_f32_e32 v57, v57, v234
	v_sub_f32_e32 v58, v58, v234
	v_sub_f32_e32 v59, v59, v234
	v_sub_f32_e32 v60, v60, v234
	v_sub_f32_e32 v61, v61, v234
	v_sub_f32_e32 v62, v62, v234
	v_sub_f32_e32 v63, v63, v234
	v_exp_f32_e32 v32, v32
	v_mfma_f32_32x32x16_bf16 v[112:127], a[156:159], v[212:215], v[112:127]
	v_exp_f32_e32 v33, v33
	v_exp_f32_e32 v34, v34
	v_exp_f32_e32 v35, v35
	v_exp_f32_e32 v36, v36
	v_exp_f32_e32 v37, v37
	v_exp_f32_e32 v38, v38
	v_exp_f32_e32 v39, v39
	v_exp_f32_e32 v40, v40
	v_exp_f32_e32 v41, v41
	v_exp_f32_e32 v42, v42
	v_exp_f32_e32 v43, v43
	v_exp_f32_e32 v44, v44
	v_exp_f32_e32 v45, v45
	v_exp_f32_e32 v46, v46
	v_exp_f32_e32 v47, v47
	v_exp_f32_e32 v48, v48
	v_exp_f32_e32 v49, v49
	v_exp_f32_e32 v50, v50
	v_exp_f32_e32 v51, v51
	v_exp_f32_e32 v52, v52
	v_exp_f32_e32 v53, v53
	v_exp_f32_e32 v54, v54
	v_exp_f32_e32 v55, v55
	v_exp_f32_e32 v56, v56
	v_exp_f32_e32 v57, v57
	v_exp_f32_e32 v58, v58
	v_exp_f32_e32 v59, v59
	v_exp_f32_e32 v60, v60
	v_exp_f32_e32 v61, v61
	v_exp_f32_e32 v62, v62
	v_exp_f32_e32 v63, v63
	v_mul_f32_e32 v23, v23, v236
	v_add_f32_e32 v238, v32, v33
	v_add_f32_e32 v238, v238, v34
	v_add_f32_e32 v238, v238, v35
	v_add_f32_e32 v238, v238, v36
	v_add_f32_e32 v238, v238, v37
	v_add_f32_e32 v238, v238, v38
	v_add_f32_e32 v238, v238, v39
	v_add_f32_e32 v238, v238, v40
	v_add_f32_e32 v238, v238, v41
	v_add_f32_e32 v238, v238, v42
	v_add_f32_e32 v238, v238, v43
	v_add_f32_e32 v238, v238, v44
	v_add_f32_e32 v238, v238, v45
	v_add_f32_e32 v238, v238, v46
	v_add_f32_e32 v238, v238, v47
	v_add_f32_e32 v238, v238, v48
	v_add_f32_e32 v238, v238, v49
	v_add_f32_e32 v238, v238, v50
	v_add_f32_e32 v238, v238, v51
	v_add_f32_e32 v238, v238, v52
	v_add_f32_e32 v238, v238, v53
	v_add_f32_e32 v238, v238, v54
	v_add_f32_e32 v238, v238, v55
	v_add_f32_e32 v238, v238, v56
	v_add_f32_e32 v238, v238, v57
	v_add_f32_e32 v238, v238, v58
	v_add_f32_e32 v238, v238, v59
	v_add_f32_e32 v238, v238, v60
	v_add_f32_e32 v238, v238, v61
	v_add_f32_e32 v238, v238, v62
	v_add_f32_e32 v238, v238, v63
	v_add_f32_e32 v23, v23, v238
	v_pk_mul_f32 v[128:129], v[128:129], v[236:237] op_sel_hi:[1,0]
	v_pk_mul_f32 v[130:131], v[130:131], v[236:237] op_sel_hi:[1,0]
	v_pk_mul_f32 v[132:133], v[132:133], v[236:237] op_sel_hi:[1,0]
	v_pk_mul_f32 v[134:135], v[134:135], v[236:237] op_sel_hi:[1,0]
	v_pk_mul_f32 v[136:137], v[136:137], v[236:237] op_sel_hi:[1,0]
	v_pk_mul_f32 v[138:139], v[138:139], v[236:237] op_sel_hi:[1,0]
	v_pk_mul_f32 v[140:141], v[140:141], v[236:237] op_sel_hi:[1,0]
	v_pk_mul_f32 v[142:143], v[142:143], v[236:237] op_sel_hi:[1,0]
	v_pk_mul_f32 v[144:145], v[144:145], v[236:237] op_sel_hi:[1,0]
	v_pk_mul_f32 v[146:147], v[146:147], v[236:237] op_sel_hi:[1,0]
	v_pk_mul_f32 v[148:149], v[148:149], v[236:237] op_sel_hi:[1,0]
	v_pk_mul_f32 v[150:151], v[150:151], v[236:237] op_sel_hi:[1,0]
	v_pk_mul_f32 v[152:153], v[152:153], v[236:237] op_sel_hi:[1,0]
	v_pk_mul_f32 v[154:155], v[154:155], v[236:237] op_sel_hi:[1,0]
	v_pk_mul_f32 v[156:157], v[156:157], v[236:237] op_sel_hi:[1,0]
	v_pk_mul_f32 v[158:159], v[158:159], v[236:237] op_sel_hi:[1,0]
	v_pk_mul_f32 v[160:161], v[160:161], v[236:237] op_sel_hi:[1,0]
	v_pk_mul_f32 v[162:163], v[162:163], v[236:237] op_sel_hi:[1,0]
	v_pk_mul_f32 v[164:165], v[164:165], v[236:237] op_sel_hi:[1,0]
	v_pk_mul_f32 v[166:167], v[166:167], v[236:237] op_sel_hi:[1,0]
	v_pk_mul_f32 v[168:169], v[168:169], v[236:237] op_sel_hi:[1,0]
	v_pk_mul_f32 v[170:171], v[170:171], v[236:237] op_sel_hi:[1,0]
	v_pk_mul_f32 v[172:173], v[172:173], v[236:237] op_sel_hi:[1,0]
	v_pk_mul_f32 v[174:175], v[174:175], v[236:237] op_sel_hi:[1,0]
	v_pk_mul_f32 v[176:177], v[176:177], v[236:237] op_sel_hi:[1,0]
	v_pk_mul_f32 v[178:179], v[178:179], v[236:237] op_sel_hi:[1,0]
	v_pk_mul_f32 v[180:181], v[180:181], v[236:237] op_sel_hi:[1,0]
	v_pk_mul_f32 v[182:183], v[182:183], v[236:237] op_sel_hi:[1,0]
	v_pk_mul_f32 v[184:185], v[184:185], v[236:237] op_sel_hi:[1,0]
	v_pk_mul_f32 v[186:187], v[186:187], v[236:237] op_sel_hi:[1,0]
	v_pk_mul_f32 v[188:189], v[188:189], v[236:237] op_sel_hi:[1,0]
	v_pk_mul_f32 v[190:191], v[190:191], v[236:237] op_sel_hi:[1,0]
	v_cvt_pk_bf16_f32 v32, v32, v33
	v_cvt_pk_bf16_f32 v33, v34, v35
	v_cvt_pk_bf16_f32 v34, v36, v37
	v_cvt_pk_bf16_f32 v35, v38, v39
	v_cvt_pk_bf16_f32 v36, v40, v41
	v_cvt_pk_bf16_f32 v37, v42, v43
	v_cvt_pk_bf16_f32 v38, v44, v45
	v_cvt_pk_bf16_f32 v39, v46, v47
	v_cvt_pk_bf16_f32 v48, v48, v49
	v_cvt_pk_bf16_f32 v49, v50, v51
	v_cvt_pk_bf16_f32 v50, v52, v53
	v_cvt_pk_bf16_f32 v51, v54, v55
	v_cvt_pk_bf16_f32 v52, v56, v57
	v_cvt_pk_bf16_f32 v53, v58, v59
	v_cvt_pk_bf16_f32 v54, v60, v61
	v_cvt_pk_bf16_f32 v55, v62, v63
	s_nop 1
	v_mfma_f32_32x32x16_bf16 v[128:143], a[96:99], v[32:35], v[128:143]
	v_mfma_f32_32x32x16_bf16 v[128:143], a[100:103], v[36:39], v[128:143]
	v_mfma_f32_32x32x16_bf16 v[144:159], a[104:107], v[32:35], v[144:159]
	v_mfma_f32_32x32x16_bf16 v[144:159], a[108:111], v[36:39], v[144:159]
	v_mfma_f32_32x32x16_bf16 v[160:175], a[112:115], v[32:35], v[160:175]
	v_mfma_f32_32x32x16_bf16 v[160:175], a[116:119], v[36:39], v[160:175]
	v_mfma_f32_32x32x16_bf16 v[176:191], a[120:123], v[32:35], v[176:191]
	v_mfma_f32_32x32x16_bf16 v[176:191], a[124:127], v[36:39], v[176:191]
	v_mfma_f32_32x32x16_bf16 v[128:143], a[128:131], v[48:51], v[128:143]
	v_mfma_f32_32x32x16_bf16 v[128:143], a[132:135], v[52:55], v[128:143]
	v_mfma_f32_32x32x16_bf16 v[144:159], a[136:139], v[48:51], v[144:159]
	v_mfma_f32_32x32x16_bf16 v[144:159], a[140:143], v[52:55], v[144:159]
	v_mfma_f32_32x32x16_bf16 v[160:175], a[144:147], v[48:51], v[160:175]
	v_mfma_f32_32x32x16_bf16 v[160:175], a[148:151], v[52:55], v[160:175]
	v_mfma_f32_32x32x16_bf16 v[176:191], a[152:155], v[48:51], v[176:191]
	v_mfma_f32_32x32x16_bf16 v[176:191], a[156:159], v[52:55], v[176:191]

.LBB0_52:
	v_ashrrev_i32_e32 v250, 5, v2
	v_mul_u32_u24_e32 v249, 0x210, v250
	v_add_u32_e32 v249, v249, v252
	v_lshlrev_b32_e32 v58, 11, v250
	v_mov_b32_e32 v59, 0
	v_lshl_add_u64 v[10:11], v[0:1], 0, v[58:59]
	v_mov_b32_e32 v58, 0x4000
	v_lshl_add_u64 v[44:45], v[10:11], 0, v[58:59]
	v_lshl_add_u64 v[46:47], v[44:45], 0, v[58:59]
	v_lshl_add_u64 v[48:49], v[46:47], 0, v[58:59]
	v_lshl_add_u64 v[50:51], v[48:49], 0, v[58:59]
	v_lshl_add_u64 v[52:53], v[50:51], 0, v[58:59]
	v_lshl_add_u64 v[54:55], v[52:53], 0, v[58:59]
	v_lshl_add_u64 v[56:57], v[54:55], 0, v[58:59]
	v_mov_b32_e32 v58, 0x20000
	s_mov_b32 s10, 0
.Lflush_f0:
	ds_read_b128 v[12:15], v249
	ds_read_b128 v[16:19], v249 offset:4224
	ds_read_b128 v[20:23], v249 offset:8448
	ds_read_b128 v[24:27], v249 offset:12672
	ds_read_b128 v[28:31], v249 offset:16896
	ds_read_b128 v[32:35], v249 offset:21120
	ds_read_b128 v[36:39], v249 offset:25344
	ds_read_b128 v[40:43], v249 offset:29568
	v_add_u32_e32 v249, 0x8400, v249
	s_waitcnt lgkmcnt(7)
	global_store_dwordx4 v[10:11], v[12:15], off
	s_waitcnt lgkmcnt(6)
	global_store_dwordx4 v[44:45], v[16:19], off
	s_waitcnt lgkmcnt(5)
	global_store_dwordx4 v[46:47], v[20:23], off
	s_waitcnt lgkmcnt(4)
	global_store_dwordx4 v[48:49], v[24:27], off
	s_waitcnt lgkmcnt(3)
	global_store_dwordx4 v[50:51], v[28:31], off
	s_waitcnt lgkmcnt(2)
	global_store_dwordx4 v[52:53], v[32:35], off
	s_waitcnt lgkmcnt(1)
	global_store_dwordx4 v[54:55], v[36:39], off
	s_waitcnt lgkmcnt(0)
	global_store_dwordx4 v[56:57], v[40:43], off
	v_lshl_add_u64 v[10:11], v[10:11], 0, v[58:59]
	v_lshl_add_u64 v[44:45], v[44:45], 0, v[58:59]
	v_lshl_add_u64 v[46:47], v[46:47], 0, v[58:59]
	v_lshl_add_u64 v[48:49], v[48:49], 0, v[58:59]
	v_lshl_add_u64 v[50:51], v[50:51], 0, v[58:59]
	v_lshl_add_u64 v[52:53], v[52:53], 0, v[58:59]
	v_lshl_add_u64 v[54:55], v[54:55], 0, v[58:59]
	v_lshl_add_u64 v[56:57], v[56:57], 0, v[58:59]
	s_add_i32 s10, s10, 1
	s_cmp_lt_u32 s10, 4
	s_cbranch_scc1 .Lflush_f0
	v_readlane_b32 s6, v254, 40
	v_readlane_b32 s7, v254, 41
	s_load_dword s6, s[6:7], 0x0
	s_waitcnt lgkmcnt(0)
	s_add_i32 s60, s6, s60
	s_cmpk_lt_i32 s60, 0x200
	s_cbranch_scc1 .LBB0_49

.LBB0_87:
	v_ashrrev_i32_e32 v250, 5, v2
	v_mul_u32_u24_e32 v249, 0x210, v250
	v_add_u32_e32 v249, v249, v252
	v_lshlrev_b32_e32 v58, 12, v250
	v_mov_b32_e32 v59, 0
	v_lshl_add_u64 v[10:11], v[0:1], 0, v[58:59]
	v_mov_b32_e32 v58, 0x8000
	v_lshl_add_u64 v[44:45], v[10:11], 0, v[58:59]
	v_lshl_add_u64 v[46:47], v[44:45], 0, v[58:59]
	v_lshl_add_u64 v[48:49], v[46:47], 0, v[58:59]
	v_lshl_add_u64 v[50:51], v[48:49], 0, v[58:59]
	v_lshl_add_u64 v[52:53], v[50:51], 0, v[58:59]
	v_lshl_add_u64 v[54:55], v[52:53], 0, v[58:59]
	v_lshl_add_u64 v[56:57], v[54:55], 0, v[58:59]
	v_mov_b32_e32 v58, 0x40000
	s_mov_b32 s4, 0
.Lflush_f1:
	ds_read_b128 v[12:15], v249
	ds_read_b128 v[16:19], v249 offset:4224
	ds_read_b128 v[20:23], v249 offset:8448
	ds_read_b128 v[24:27], v249 offset:12672
	ds_read_b128 v[28:31], v249 offset:16896
	ds_read_b128 v[32:35], v249 offset:21120
	ds_read_b128 v[36:39], v249 offset:25344
	ds_read_b128 v[40:43], v249 offset:29568
	v_add_u32_e32 v249, 0x8400, v249
	s_waitcnt lgkmcnt(7)
	global_store_dwordx4 v[10:11], v[12:15], off
	s_waitcnt lgkmcnt(6)
	global_store_dwordx4 v[44:45], v[16:19], off
	s_waitcnt lgkmcnt(5)
	global_store_dwordx4 v[46:47], v[20:23], off
	s_waitcnt lgkmcnt(4)
	global_store_dwordx4 v[48:49], v[24:27], off
	s_waitcnt lgkmcnt(3)
	global_store_dwordx4 v[50:51], v[28:31], off
	s_waitcnt lgkmcnt(2)
	global_store_dwordx4 v[52:53], v[32:35], off
	s_waitcnt lgkmcnt(1)
	global_store_dwordx4 v[54:55], v[36:39], off
	s_waitcnt lgkmcnt(0)
	global_store_dwordx4 v[56:57], v[40:43], off
	v_lshl_add_u64 v[10:11], v[10:11], 0, v[58:59]
	v_lshl_add_u64 v[44:45], v[44:45], 0, v[58:59]
	v_lshl_add_u64 v[46:47], v[46:47], 0, v[58:59]
	v_lshl_add_u64 v[48:49], v[48:49], 0, v[58:59]
	v_lshl_add_u64 v[50:51], v[50:51], 0, v[58:59]
	v_lshl_add_u64 v[52:53], v[52:53], 0, v[58:59]
	v_lshl_add_u64 v[54:55], v[54:55], 0, v[58:59]
	v_lshl_add_u64 v[56:57], v[56:57], 0, v[58:59]
	s_add_i32 s4, s4, 1
	s_cmp_lt_u32 s4, 4
	s_cbranch_scc1 .Lflush_f1
	s_mov_b64 s[4:5], 0

.Lflush_f2:
	ds_read_b128 v[12:15], v249
	ds_read_b128 v[16:19], v249 offset:4224
	ds_read_b128 v[20:23], v249 offset:8448
	ds_read_b128 v[24:27], v249 offset:12672
	ds_read_b128 v[28:31], v249 offset:16896
	ds_read_b128 v[32:35], v249 offset:21120
	ds_read_b128 v[36:39], v249 offset:25344
	ds_read_b128 v[40:43], v249 offset:29568
	v_add_u32_e32 v249, 0x8400, v249
	s_waitcnt lgkmcnt(7)
	global_store_dwordx4 v[10:11], v[12:15], off
	s_waitcnt lgkmcnt(6)
	global_store_dwordx4 v[44:45], v[16:19], off
	s_waitcnt lgkmcnt(5)
	global_store_dwordx4 v[46:47], v[20:23], off
	s_waitcnt lgkmcnt(4)
	global_store_dwordx4 v[48:49], v[24:27], off
	s_waitcnt lgkmcnt(3)
	global_store_dwordx4 v[50:51], v[28:31], off
	s_waitcnt lgkmcnt(2)
	global_store_dwordx4 v[52:53], v[32:35], off
	s_waitcnt lgkmcnt(1)
	global_store_dwordx4 v[54:55], v[36:39], off
	s_waitcnt lgkmcnt(0)
	global_store_dwordx4 v[56:57], v[40:43], off
	v_lshl_add_u64 v[10:11], v[10:11], 0, v[58:59]
	v_lshl_add_u64 v[44:45], v[44:45], 0, v[58:59]
	v_lshl_add_u64 v[46:47], v[46:47], 0, v[58:59]
	v_lshl_add_u64 v[48:49], v[48:49], 0, v[58:59]
	v_lshl_add_u64 v[50:51], v[50:51], 0, v[58:59]
	v_lshl_add_u64 v[52:53], v[52:53], 0, v[58:59]
	v_lshl_add_u64 v[54:55], v[54:55], 0, v[58:59]
	v_lshl_add_u64 v[56:57], v[56:57], 0, v[58:59]
	s_add_i32 s10, s10, 1
	s_cmp_lt_u32 s10, 4
	s_cbranch_scc1 .Lflush_f2
	s_branch .LBB0_82

.Lflush_f3:
	ds_read_b128 v[12:15], v249
	ds_read_b128 v[16:19], v249 offset:4224
	ds_read_b128 v[20:23], v249 offset:8448
	ds_read_b128 v[24:27], v249 offset:12672
	ds_read_b128 v[28:31], v249 offset:16896
	ds_read_b128 v[32:35], v249 offset:21120
	ds_read_b128 v[36:39], v249 offset:25344
	ds_read_b128 v[40:43], v249 offset:29568
	v_add_u32_e32 v249, 0x8400, v249
	s_waitcnt lgkmcnt(7)
	global_store_dwordx4 v[10:11], v[12:15], off
	s_waitcnt lgkmcnt(6)
	global_store_dwordx4 v[44:45], v[16:19], off
	s_waitcnt lgkmcnt(5)
	global_store_dwordx4 v[46:47], v[20:23], off
	s_waitcnt lgkmcnt(4)
	global_store_dwordx4 v[48:49], v[24:27], off
	s_waitcnt lgkmcnt(3)
	global_store_dwordx4 v[50:51], v[28:31], off
	s_waitcnt lgkmcnt(2)
	global_store_dwordx4 v[52:53], v[32:35], off
	s_waitcnt lgkmcnt(1)
	global_store_dwordx4 v[54:55], v[36:39], off
	s_waitcnt lgkmcnt(0)
	global_store_dwordx4 v[56:57], v[40:43], off
	v_lshl_add_u64 v[10:11], v[10:11], 0, v[58:59]
	v_lshl_add_u64 v[44:45], v[44:45], 0, v[58:59]
	v_lshl_add_u64 v[46:47], v[46:47], 0, v[58:59]
	v_lshl_add_u64 v[48:49], v[48:49], 0, v[58:59]
	v_lshl_add_u64 v[50:51], v[50:51], 0, v[58:59]
	v_lshl_add_u64 v[52:53], v[52:53], 0, v[58:59]
	v_lshl_add_u64 v[54:55], v[54:55], 0, v[58:59]
	v_lshl_add_u64 v[56:57], v[56:57], 0, v[58:59]
	s_add_i32 s10, s10, 1
	s_cmp_lt_u32 s10, 4
	s_cbranch_scc1 .Lflush_f3
	v_readlane_b32 s4, v254, 40
	v_readlane_b32 s5, v254, 41
	s_load_dword s4, s[4:5], 0x0
	v_mov_b32_e32 v251, 0x3727c5ac
	s_waitcnt lgkmcnt(0)
	s_add_i32 s42, s4, s42
	s_cmpk_lt_i32 s42, 0x200
	s_cbranch_scc1 .LBB0_96

.LBB0_150:
	v_ashrrev_i32_e32 v249, 4, v226
	v_mul_u32_u24_e32 v248, 0x110, v249
	v_add_u32_e32 v248, v248, v252
	v_lshlrev_b32_e32 v232, 8, v249
	v_mov_b32_e32 v233, 0
	v_lshl_add_u64 v[232:233], v[224:225], 0, v[232:233]
	v_mov_b32_e32 v234, 0x1000
	v_mov_b32_e32 v235, 0
	s_mov_b32 s4, 0
.Lroute_stage:
	global_load_dwordx4 v[228:231], v[232:233], off
	v_lshl_add_u64 v[232:233], v[232:233], 0, v[234:235]
	global_load_dwordx4 v[236:239], v[232:233], off
	v_lshl_add_u64 v[232:233], v[232:233], 0, v[234:235]
	global_load_dwordx4 v[240:243], v[232:233], off
	v_lshl_add_u64 v[232:233], v[232:233], 0, v[234:235]
	global_load_dwordx4 v[244:247], v[232:233], off
	v_lshl_add_u64 v[232:233], v[232:233], 0, v[234:235]
	s_waitcnt vmcnt(3)
	ds_write_b128 v248, v[228:231]
	s_waitcnt vmcnt(2)
	ds_write_b128 v248, v[236:239] offset:4352
	s_waitcnt vmcnt(1)
	ds_write_b128 v248, v[240:243] offset:8704
	s_waitcnt vmcnt(0)
	ds_write_b128 v248, v[244:247] offset:13056
	v_add_u32_e32 v248, 0x4400, v248
	s_add_i32 s4, s4, 1
	s_cmp_lt_u32 s4, 4
	s_cbranch_scc1 .Lroute_stage
	v_mfma_f32_32x32x16_bf16 a[96:111], v[148:151], v[132:135], a[96:111]
	s_mov_b32 s4, s35
	s_waitcnt lgkmcnt(0)
	s_barrier
	v_cvt_pk_bf16_f32 v112, v112, v113
	v_cvt_pk_bf16_f32 v113, v114, v115
	v_mfma_f32_32x32x16_bf16 a[32:47], v[148:151], v[140:143], a[32:47]
	v_cvt_pk_bf16_f32 v114, v116, v117
	v_cvt_pk_bf16_f32 v115, v118, v119
	v_cvt_pk_bf16_f32 v116, v120, v121
	v_cvt_pk_bf16_f32 v117, v122, v123
	v_cvt_pk_bf16_f32 v118, v124, v125
	v_cvt_pk_bf16_f32 v119, v126, v127
	v_cvt_pk_bf16_f32 v96, v96, v97
	v_mfma_f32_32x32x16_bf16 a[96:111], v[172:175], v[156:159], a[96:111]
	v_cvt_pk_bf16_f32 v97, v98, v99
	v_cvt_pk_bf16_f32 v98, v100, v101
	v_cvt_pk_bf16_f32 v99, v102, v103
	v_cvt_pk_bf16_f32 v100, v104, v105
	v_cvt_pk_bf16_f32 v101, v106, v107
	v_cvt_pk_bf16_f32 v102, v108, v109
	v_cvt_pk_bf16_f32 v103, v110, v111
	v_mfma_f32_32x32x16_bf16 a[32:47], v[172:175], v[164:167], a[32:47]
	v_cvt_pk_bf16_f32 v80, v80, v81
	v_cvt_pk_bf16_f32 v81, v82, v83
	v_cvt_pk_bf16_f32 v82, v84, v85
	v_cvt_pk_bf16_f32 v83, v86, v87
	v_cvt_pk_bf16_f32 v84, v88, v89
	v_cvt_pk_bf16_f32 v85, v90, v91
	v_cvt_pk_bf16_f32 v86, v92, v93
	v_mfma_f32_32x32x16_bf16 a[64:79], v[128:131], v[132:135], a[64:79]
	v_cvt_pk_bf16_f32 v87, v94, v95
	v_cvt_pk_bf16_f32 v64, v64, v65
	v_cvt_pk_bf16_f32 v65, v66, v67
	v_cvt_pk_bf16_f32 v66, v68, v69
	v_cvt_pk_bf16_f32 v67, v70, v71
	v_cvt_pk_bf16_f32 v68, v72, v73
	v_cvt_pk_bf16_f32 v69, v74, v75
	v_mfma_f32_32x32x16_bf16 a[0:15], v[128:131], v[140:143], a[0:15]
	v_mbcnt_lo_u32_b32 v128, -1, s4
	v_mbcnt_hi_u32_b32 v128, -1, v128
	v_mov_b32_e32 v129, s30
	s_mov_b32 s4, 0xfffff9f
	v_or_b32_e32 v131, s30, v128
	v_cvt_pk_bf16_f32 v70, v76, v77
	v_cvt_pk_bf16_f32 v71, v78, v79
	v_mfma_f32_32x32x16_bf16 a[80:95], v[136:139], v[132:135], a[80:95]
	v_mfma_f32_32x32x16_bf16 a[112:127], v[144:147], v[132:135], a[112:127]
	v_and_b32_e32 v132, 31, v128
	v_bfe_u32 v133, v128, 5, 1
	v_bitop3_b32 v128, v128, s4, v129 bitop3:0xc8
	v_mul_lo_u32 v128, v128, s23
	v_lshl_or_b32 v130, v133, 3, v128
	v_lshlrev_b32_e32 v128, 1, v131
	s_mov_b32 s4, 0x3ffff80
	v_and_or_b32 v128, v128, s4, v132
	v_mov_b32_e32 v132, v253
	v_mfma_f32_32x32x16_bf16 a[96:111], v[196:199], v[180:183], a[96:111]
	v_cmp_eq_u32_e32 vcc, 0, v133
	v_add_u32_e32 v131, 0x2000, v130
	v_mov_b32_e32 v134, v132
	v_mov_b32_e32 v135, v132
	s_mov_b32 s4, s35
	v_mfma_f32_32x32x16_bf16 a[32:47], v[196:199], v[188:191], a[32:47]
	v_lshlrev_b32_e32 v196, 2, v133
	v_mov_b32_e32 v133, v132
	v_xor_b32_e32 v172, 52, v196
	v_xor_b32_e32 v173, 47, v196
	v_xor_b32_e32 v174, 46, v196
	v_xor_b32_e32 v175, 45, v196
	v_xor_b32_e32 v129, 0x7f, v196
	v_mfma_f32_32x32x16_bf16 a[176:191], v[132:135], v[132:135], 0
	v_mov_b32_e32 v132, v253
	v_xor_b32_e32 v148, 0x65, v196
	v_mov_b32_e32 v133, v132
	v_mov_b32_e32 v134, v132
	v_mov_b32_e32 v135, v132
	v_xor_b32_e32 v149, 0x5f, v196
	v_mfma_f32_32x32x16_bf16 a[64:79], v[152:155], v[156:159], a[64:79]
	v_xor_b32_e32 v150, 0x5e, v196
	v_xor_b32_e32 v151, 0x5d, v196
	v_mfma_f32_32x32x16_bf16 a[160:175], v[132:135], v[132:135], 0
	v_mov_b32_e32 v132, v253
	s_nop 0
	v_mov_b32_e32 v133, v132
	v_mov_b32_e32 v134, v132
	v_mov_b32_e32 v135, v132
	v_mfma_f32_32x32x16_bf16 a[80:95], v[160:163], v[156:159], a[80:95]
	s_nop 0
	v_mfma_f32_32x32x16_bf16 a[144:159], v[132:135], v[132:135], 0
	v_mov_b32_e32 v132, v253
	ds_read2_b64 v[120:123], v130 offset1:2
	ds_read2_b64 v[124:127], v130 offset0:4 offset1:6
	v_mov_b32_e32 v133, v132
	v_mov_b32_e32 v134, v132
	v_mov_b32_e32 v135, v132
	s_waitcnt lgkmcnt(1)
	v_mfma_f32_32x32x16_bf16 a[176:191], v[120:123], v[112:115], a[176:191]
	s_waitcnt lgkmcnt(0)
	v_mfma_f32_32x32x16_bf16 a[176:191], v[124:127], v[116:119], a[176:191]
	ds_read2_b64 v[120:123], v131 offset0:64 offset1:66
	ds_read2_b64 v[124:127], v131 offset0:68 offset1:70
	s_waitcnt lgkmcnt(1)
	v_mfma_f32_32x32x16_bf16 a[160:175], v[120:123], v[112:115], a[160:175]
	v_mfma_f32_32x32x16_bf16 a[128:143], v[132:135], v[132:135], 0
	v_add_u32_e32 v133, 0x4000, v130
	v_add_u32_e32 v132, 0x6000, v130
	v_xor_b32_e32 v134, 0x7e, v196
	v_xor_b32_e32 v135, 0x7d, v196
	s_waitcnt lgkmcnt(0)
	v_mfma_f32_32x32x16_bf16 a[160:175], v[124:127], v[116:119], a[160:175]
	ds_read2_b64 v[120:123], v133 offset0:128 offset1:130
	ds_read2_b64 v[124:127], v133 offset0:132 offset1:134
	s_waitcnt lgkmcnt(1)
	v_mfma_f32_32x32x16_bf16 a[144:159], v[120:123], v[112:115], a[144:159]
	s_waitcnt lgkmcnt(0)
	v_mfma_f32_32x32x16_bf16 a[144:159], v[124:127], v[116:119], a[144:159]
	ds_read2_b64 v[120:123], v132 offset0:192 offset1:194
	ds_read2_b64 v[124:127], v132 offset0:196 offset1:198
	ds_read2_b64 v[104:107], v130 offset0:8 offset1:10
	ds_read2_b64 v[108:111], v130 offset0:12 offset1:14
	s_waitcnt lgkmcnt(1)
	v_mfma_f32_32x32x16_bf16 a[176:191], v[104:107], v[96:99], a[176:191]
	s_waitcnt lgkmcnt(0)
	v_mfma_f32_32x32x16_bf16 a[176:191], v[108:111], v[100:103], a[176:191]
	ds_read2_b64 v[104:107], v131 offset0:72 offset1:74
	ds_read2_b64 v[108:111], v131 offset0:76 offset1:78
	s_waitcnt lgkmcnt(1)
	v_mfma_f32_32x32x16_bf16 a[160:175], v[104:107], v[96:99], a[160:175]
	s_waitcnt lgkmcnt(0)
	v_mfma_f32_32x32x16_bf16 a[160:175], v[108:111], v[100:103], a[160:175]
	ds_read2_b64 v[104:107], v133 offset0:136 offset1:138
	ds_read2_b64 v[108:111], v133 offset0:140 offset1:142
	s_waitcnt lgkmcnt(1)
	v_mfma_f32_32x32x16_bf16 a[144:159], v[104:107], v[96:99], a[144:159]
	s_waitcnt lgkmcnt(0)
	v_mfma_f32_32x32x16_bf16 a[144:159], v[108:111], v[100:103], a[144:159]
	ds_read2_b64 v[104:107], v132 offset0:200 offset1:202
	ds_read2_b64 v[108:111], v132 offset0:204 offset1:206
	ds_read2_b64 v[88:91], v130 offset0:16 offset1:18
	ds_read2_b64 v[92:95], v130 offset0:20 offset1:22
	s_waitcnt lgkmcnt(1)
	v_mfma_f32_32x32x16_bf16 a[176:191], v[88:91], v[80:83], a[176:191]
	s_waitcnt lgkmcnt(0)
	v_mfma_f32_32x32x16_bf16 a[176:191], v[92:95], v[84:87], a[176:191]
	ds_read2_b64 v[88:91], v131 offset0:80 offset1:82
	ds_read2_b64 v[92:95], v131 offset0:84 offset1:86
	s_waitcnt lgkmcnt(1)
	v_mfma_f32_32x32x16_bf16 a[160:175], v[88:91], v[80:83], a[160:175]
	s_waitcnt lgkmcnt(0)
	v_mfma_f32_32x32x16_bf16 a[160:175], v[92:95], v[84:87], a[160:175]
	ds_read2_b64 v[88:91], v133 offset0:144 offset1:146
	ds_read2_b64 v[92:95], v133 offset0:148 offset1:150
	s_waitcnt lgkmcnt(1)
	v_mfma_f32_32x32x16_bf16 a[144:159], v[88:91], v[80:83], a[144:159]
	s_waitcnt lgkmcnt(0)
	v_mfma_f32_32x32x16_bf16 a[144:159], v[92:95], v[84:87], a[144:159]
	ds_read2_b64 v[88:91], v132 offset0:208 offset1:210
	ds_read2_b64 v[92:95], v132 offset0:212 offset1:214
	ds_read2_b64 v[72:75], v130 offset0:24 offset1:26
	ds_read2_b64 v[76:79], v130 offset0:28 offset1:30
	s_waitcnt lgkmcnt(1)
	v_mfma_f32_32x32x16_bf16 a[176:191], v[72:75], v[64:67], a[176:191]
	s_waitcnt lgkmcnt(0)
	v_mfma_f32_32x32x16_bf16 a[176:191], v[76:79], v[68:71], a[176:191]
	ds_read2_b64 v[72:75], v131 offset0:88 offset1:90
	ds_read2_b64 v[76:79], v131 offset0:92 offset1:94
	s_waitcnt lgkmcnt(1)
	v_mfma_f32_32x32x16_bf16 a[160:175], v[72:75], v[64:67], a[160:175]
	v_mfma_f32_32x32x16_bf16 a[128:143], v[120:123], v[112:115], a[128:143]
	s_waitcnt lgkmcnt(0)
	v_mfma_f32_32x32x16_bf16 a[160:175], v[76:79], v[68:71], a[160:175]
	ds_read2_b64 v[72:75], v133 offset0:152 offset1:154
	ds_read2_b64 v[76:79], v133 offset0:156 offset1:158
	s_waitcnt lgkmcnt(1)
	v_mfma_f32_32x32x16_bf16 a[144:159], v[72:75], v[64:67], a[144:159]
	v_mfma_f32_32x32x16_bf16 a[128:143], v[124:127], v[116:119], a[128:143]
	s_waitcnt lgkmcnt(0)
	v_mfma_f32_32x32x16_bf16 a[144:159], v[76:79], v[68:71], a[144:159]
	ds_read2_b64 v[72:75], v132 offset0:216 offset1:218
	ds_read2_b64 v[76:79], v132 offset0:220 offset1:222
	v_mfma_f32_32x32x16_bf16 a[128:143], v[104:107], v[96:99], a[128:143]
	s_nop 8
	v_accvgpr_read_b32 v112, a144
	v_ashrrev_i32_e32 v113, 31, v112
	v_bitop3_b32 v112, v113, v112, s75 bitop3:0x36
	v_mfma_f32_32x32x16_bf16 a[128:143], v[108:111], v[100:103], a[128:143]
	v_accvgpr_read_b32 v113, a145
	v_ashrrev_i32_e32 v114, 31, v113
	v_bitop3_b32 v113, v114, v113, s75 bitop3:0x36
	v_accvgpr_read_b32 v114, a146
	v_ashrrev_i32_e32 v115, 31, v114
	v_bitop3_b32 v114, v115, v114, s75 bitop3:0x36
	v_accvgpr_read_b32 v115, a147
	v_ashrrev_i32_e32 v116, 31, v115
	v_bitop3_b32 v115, v116, v115, s75 bitop3:0x36
	v_accvgpr_read_b32 v116, a148
	v_ashrrev_i32_e32 v117, 31, v116
	v_mfma_f32_32x32x16_bf16 a[128:143], v[88:91], v[80:83], a[128:143]
	v_bitop3_b32 v116, v117, v116, s75 bitop3:0x36
	v_accvgpr_read_b32 v117, a149
	v_ashrrev_i32_e32 v118, 31, v117
	v_bitop3_b32 v117, v118, v117, s75 bitop3:0x36
	v_accvgpr_read_b32 v118, a150
	v_ashrrev_i32_e32 v119, 31, v118
	v_bitop3_b32 v118, v119, v118, s75 bitop3:0x36
	v_accvgpr_read_b32 v119, a151
	v_ashrrev_i32_e32 v120, 31, v119
	v_bitop3_b32 v119, v120, v119, s75 bitop3:0x36
	v_accvgpr_read_b32 v120, a152
	v_ashrrev_i32_e32 v121, 31, v120
	v_mfma_f32_32x32x16_bf16 a[128:143], v[92:95], v[84:87], a[128:143]
	v_bitop3_b32 v120, v121, v120, s75 bitop3:0x36
	v_accvgpr_read_b32 v121, a153
	v_ashrrev_i32_e32 v122, 31, v121
	v_bitop3_b32 v121, v122, v121, s75 bitop3:0x36
	v_accvgpr_read_b32 v122, a154
	v_ashrrev_i32_e32 v123, 31, v122
	v_bitop3_b32 v122, v123, v122, s75 bitop3:0x36
	v_accvgpr_read_b32 v123, a155
	v_mfma_f32_32x32x16_bf16 a[112:127], v[168:171], v[156:159], a[112:127]
	v_ashrrev_i32_e32 v124, 31, v123
	v_bitop3_b32 v123, v124, v123, s75 bitop3:0x36
	v_accvgpr_read_b32 v124, a156
	v_ashrrev_i32_e32 v125, 31, v124
	v_bitop3_b32 v124, v125, v124, s75 bitop3:0x36
	v_accvgpr_read_b32 v125, a157
	v_ashrrev_i32_e32 v126, 31, v125
	v_mfma_f32_32x32x16_bf16 a[16:31], v[136:139], v[140:143], a[16:31]
	v_bitop3_b32 v125, v126, v125, s75 bitop3:0x36
	v_accvgpr_read_b32 v126, a158
	v_ashrrev_i32_e32 v127, 31, v126
	v_bitop3_b32 v126, v127, v126, s75 bitop3:0x36
	v_accvgpr_read_b32 v127, a159
	v_and_or_b32 v119, v119, s33, v172
	v_and_or_b32 v120, v120, s33, v173
	v_mfma_f32_32x32x16_bf16 a[48:63], v[144:147], v[140:143], a[48:63]
	v_and_or_b32 v121, v121, s33, v174
	v_and_or_b32 v122, v122, s33, v175
	v_accvgpr_read_b32 v88, a160
	v_ashrrev_i32_e32 v89, 31, v88
	v_bitop3_b32 v88, v89, v88, s75 bitop3:0x36
	v_accvgpr_read_b32 v89, a161
	v_ashrrev_i32_e32 v90, 31, v89
	v_mfma_f32_32x32x16_bf16 a[0:15], v[152:155], v[164:167], a[0:15]
	v_bitop3_b32 v89, v90, v89, s75 bitop3:0x36
	v_accvgpr_read_b32 v90, a162
	v_ashrrev_i32_e32 v91, 31, v90
	v_bitop3_b32 v90, v91, v90, s75 bitop3:0x36
	v_accvgpr_read_b32 v91, a163
	v_ashrrev_i32_e32 v92, 31, v91
	v_bitop3_b32 v91, v92, v91, s75 bitop3:0x36
	s_waitcnt lgkmcnt(1)
	v_mfma_f32_32x32x16_bf16 a[128:143], v[72:75], v[64:67], a[128:143]
	v_accvgpr_read_b32 v64, a176
	v_ashrrev_i32_e32 v65, 31, v64
	v_bitop3_b32 v64, v65, v64, s75 bitop3:0x36
	v_accvgpr_read_b32 v65, a177
	v_ashrrev_i32_e32 v66, 31, v65
	v_bitop3_b32 v65, v66, v65, s75 bitop3:0x36
	v_accvgpr_read_b32 v66, a178
	v_mfma_f32_32x32x16_bf16 a[64:79], v[176:179], v[180:183], a[64:79]
	v_ashrrev_i32_e32 v67, 31, v66
	v_bitop3_b32 v66, v67, v66, s75 bitop3:0x36
	v_accvgpr_read_b32 v67, a179
	v_accvgpr_read_b32 v92, a164
	v_ashrrev_i32_e32 v93, 31, v92
	v_bitop3_b32 v92, v93, v92, s75 bitop3:0x36
	v_accvgpr_read_b32 v93, a165
	v_mfma_f32_32x32x16_bf16 a[80:95], v[184:187], v[180:183], a[80:95]
	v_ashrrev_i32_e32 v94, 31, v93
	v_bitop3_b32 v93, v94, v93, s75 bitop3:0x36
	v_accvgpr_read_b32 v94, a166
	v_ashrrev_i32_e32 v95, 31, v94
	v_bitop3_b32 v94, v95, v94, s75 bitop3:0x36
	v_accvgpr_read_b32 v95, a167
	v_ashrrev_i32_e32 v96, 31, v95
	v_mfma_f32_32x32x16_bf16 a[112:127], v[192:195], v[180:183], a[112:127]
	v_ashrrev_i32_e32 v180, 31, v127
	v_bitop3_b32 v127, v180, v127, s75 bitop3:0x36
	v_xor_b32_e32 v180, 36, v196
	v_and_or_b32 v127, v127, s33, v180
	v_bitop3_b32 v95, v96, v95, s75 bitop3:0x36
	v_accvgpr_read_b32 v96, a168
	v_ashrrev_i32_e32 v97, 31, v96
	v_mfma_f32_32x32x16_bf16 a[16:31], v[160:163], v[164:167], a[16:31]
	v_bitop3_b32 v96, v97, v96, s75 bitop3:0x36
	v_accvgpr_read_b32 v97, a169
	v_ashrrev_i32_e32 v98, 31, v97
	v_bitop3_b32 v97, v98, v97, s75 bitop3:0x36
	v_accvgpr_read_b32 v98, a170
	v_ashrrev_i32_e32 v99, 31, v98
	v_bitop3_b32 v98, v99, v98, s75 bitop3:0x36
	v_mfma_f32_32x32x16_bf16 a[48:63], v[168:171], v[164:167], a[48:63]
	v_xor_b32_e32 v165, 63, v196
	v_xor_b32_e32 v166, 62, v196
	v_xor_b32_e32 v167, 61, v196
	v_xor_b32_e32 v168, 60, v196
	v_xor_b32_e32 v169, 55, v196
	v_xor_b32_e32 v170, 54, v196
	v_xor_b32_e32 v171, 53, v196
	v_mfma_f32_32x32x16_bf16 a[0:15], v[176:179], v[188:191], a[0:15]
	v_xor_b32_e32 v176, 44, v196
	v_xor_b32_e32 v177, 39, v196
	v_xor_b32_e32 v178, 38, v196
	v_xor_b32_e32 v179, 37, v196
	v_and_or_b32 v112, v112, s33, v165
	v_and_or_b32 v113, v113, s33, v166
	v_and_or_b32 v114, v114, s33, v167
	v_and_or_b32 v115, v115, s33, v168
	v_and_or_b32 v116, v116, s33, v169
	v_and_or_b32 v117, v117, s33, v170
	v_and_or_b32 v118, v118, s33, v171
	v_and_or_b32 v123, v123, s33, v176
	v_and_or_b32 v124, v124, s33, v177
	v_and_or_b32 v125, v125, s33, v178
	v_and_or_b32 v126, v126, s33, v179
	s_waitcnt lgkmcnt(0)
	v_mfma_f32_32x32x16_bf16 a[128:143], v[76:79], v[68:71], a[128:143]
	v_max_u32_e32 v181, v112, v113
	v_min_u32_e32 v112, v112, v113
	v_max_u32_e32 v113, v114, v115
	v_min_u32_e32 v114, v114, v115
	v_max_u32_e32 v115, v116, v117
	v_min_u32_e32 v116, v116, v117
	v_max_u32_e32 v117, v118, v119
	v_min_u32_e32 v118, v118, v119
	v_max_u32_e32 v119, v120, v121
	v_min_u32_e32 v120, v120, v121
	v_max_u32_e32 v121, v122, v123
	v_min_u32_e32 v122, v122, v123
	v_max_u32_e32 v123, v124, v125
	v_min_u32_e32 v124, v124, v125
	v_max_u32_e32 v125, v126, v127
	v_min_u32_e32 v126, v126, v127
	v_max_u32_e32 v127, v181, v114
	v_min_u32_e32 v114, v181, v114
	v_max_u32_e32 v181, v112, v113
	v_min_u32_e32 v112, v112, v113
	v_max_u32_e32 v113, v115, v118
	v_min_u32_e32 v115, v115, v118
	v_max_u32_e32 v118, v116, v117
	v_min_u32_e32 v116, v116, v117
	v_max_u32_e32 v117, v119, v122
	v_min_u32_e32 v119, v119, v122
	v_max_u32_e32 v122, v120, v121
	v_min_u32_e32 v120, v120, v121
	v_max_u32_e32 v121, v123, v126
	v_min_u32_e32 v123, v123, v126
	v_max_u32_e32 v126, v124, v125
	v_min_u32_e32 v124, v124, v125
	v_max_u32_e32 v125, v127, v181
	v_min_u32_e32 v127, v127, v181
	v_max_u32_e32 v181, v114, v112
	v_min_u32_e32 v112, v114, v112
	v_max_u32_e32 v114, v115, v116
	v_min_u32_e32 v115, v115, v116
	v_max_u32_e32 v116, v113, v118
	v_min_u32_e32 v113, v113, v118
	v_max_u32_e32 v118, v117, v122
	v_min_u32_e32 v117, v117, v122
	v_max_u32_e32 v122, v119, v120
	v_min_u32_e32 v119, v119, v120
	v_max_u32_e32 v120, v123, v124
	v_min_u32_e32 v123, v123, v124
	v_max_u32_e32 v124, v121, v126
	v_min_u32_e32 v121, v121, v126
	v_max_u32_e32 v126, v125, v115
	v_min_u32_e32 v115, v125, v115
	v_max_u32_e32 v125, v127, v114
	v_min_u32_e32 v114, v127, v114
	v_max_u32_e32 v127, v181, v113
	v_min_u32_e32 v113, v181, v113
	v_max_u32_e32 v181, v112, v116
	v_min_u32_e32 v112, v112, v116
	v_max_u32_e32 v116, v118, v123
	v_min_u32_e32 v118, v118, v123
	v_max_u32_e32 v123, v117, v120
	v_min_u32_e32 v117, v117, v120
	v_max_u32_e32 v120, v122, v121
	v_min_u32_e32 v121, v122, v121
	v_max_u32_e32 v122, v119, v124
	v_min_u32_e32 v119, v119, v124
	v_max_u32_e32 v124, v126, v127
	v_min_u32_e32 v126, v126, v127
	v_max_u32_e32 v127, v125, v181
	v_min_u32_e32 v125, v125, v181
	v_max_u32_e32 v181, v115, v113
	v_min_u32_e32 v113, v115, v113
	v_max_u32_e32 v115, v114, v112
	v_min_u32_e32 v112, v114, v112
	v_max_u32_e32 v114, v118, v121
	v_min_u32_e32 v118, v118, v121
	v_max_u32_e32 v121, v117, v119
	v_min_u32_e32 v117, v117, v119
	v_max_u32_e32 v119, v116, v120
	v_min_u32_e32 v116, v116, v120
	v_max_u32_e32 v120, v123, v122
	v_min_u32_e32 v122, v123, v122
	v_max_u32_e32 v123, v124, v127
	v_min_u32_e32 v124, v124, v127
	v_max_u32_e32 v127, v126, v125
	v_min_u32_e32 v125, v126, v125
	v_max_u32_e32 v126, v181, v115
	v_min_u32_e32 v115, v181, v115
	v_max_u32_e32 v181, v113, v112
	v_min_u32_e32 v112, v113, v112
	v_max_u32_e32 v113, v118, v117
	v_min_u32_e32 v117, v118, v117
	v_max_u32_e32 v118, v114, v121
	v_min_u32_e32 v114, v114, v121
	v_max_u32_e32 v121, v116, v122
	v_min_u32_e32 v116, v116, v122
	v_max_u32_e32 v122, v119, v120
	v_min_u32_e32 v119, v119, v120
	v_max_u32_e32 v120, v123, v117
	v_min_u32_e32 v117, v123, v117
	v_max_u32_e32 v123, v124, v113
	v_min_u32_e32 v113, v124, v113
	v_max_u32_e32 v124, v127, v114
	v_min_u32_e32 v114, v127, v114
	v_max_u32_e32 v127, v125, v118
	v_min_u32_e32 v118, v125, v118
	v_max_u32_e32 v125, v126, v116
	v_min_u32_e32 v116, v126, v116
	v_max_u32_e32 v126, v115, v121
	v_min_u32_e32 v115, v115, v121
	v_max_u32_e32 v121, v181, v119
	v_min_u32_e32 v119, v181, v119
	v_max_u32_e32 v181, v112, v122
	v_min_u32_e32 v112, v112, v122
	v_max_u32_e32 v122, v120, v125
	v_min_u32_e32 v120, v120, v125
	v_max_u32_e32 v125, v123, v126
	v_min_u32_e32 v123, v123, v126
	v_max_u32_e32 v126, v124, v121
	v_min_u32_e32 v121, v124, v121
	v_max_u32_e32 v124, v127, v181
	v_min_u32_e32 v127, v127, v181
	v_max_u32_e32 v181, v117, v116
	v_min_u32_e32 v116, v117, v116
	v_max_u32_e32 v117, v113, v115
	v_min_u32_e32 v113, v113, v115
	v_max_u32_e32 v115, v114, v119
	v_min_u32_e32 v114, v114, v119
	v_max_u32_e32 v119, v118, v112
	v_min_u32_e32 v112, v118, v112
	v_max_u32_e32 v118, v122, v126
	v_min_u32_e32 v122, v122, v126
	v_max_u32_e32 v126, v125, v124
	v_min_u32_e32 v124, v125, v124
	v_max_u32_e32 v125, v120, v121
	v_min_u32_e32 v120, v120, v121
	v_max_u32_e32 v121, v123, v127
	v_min_u32_e32 v123, v123, v127
	v_max_u32_e32 v127, v181, v115
	v_min_u32_e32 v115, v181, v115
	v_accvgpr_read_b32 v181, a128
	v_ashrrev_i32_e32 v182, 31, v181
	v_bitop3_b32 v182, v182, v181, s75 bitop3:0x36
	v_xor_b32_e32 v181, 31, v196
	v_mfma_f32_32x32x16_bf16 a[64:79], v[200:203], v[204:207], a[64:79]
	v_ashrrev_i32_e32 v68, 31, v67
	v_bitop3_b32 v67, v68, v67, s75 bitop3:0x36
	v_accvgpr_read_b32 v68, a180
	v_ashrrev_i32_e32 v69, 31, v68
	v_bitop3_b32 v68, v69, v68, s75 bitop3:0x36
	v_accvgpr_read_b32 v69, a181
	v_ashrrev_i32_e32 v70, 31, v69
	v_mfma_f32_32x32x16_bf16 a[80:95], v[208:211], v[204:207], a[80:95]
	v_bitop3_b32 v69, v70, v69, s75 bitop3:0x36
	v_accvgpr_read_b32 v70, a182
	v_ashrrev_i32_e32 v71, 31, v70
	v_bitop3_b32 v70, v71, v70, s75 bitop3:0x36
	v_accvgpr_read_b32 v71, a183
	v_ashrrev_i32_e32 v72, 31, v71
	v_bitop3_b32 v71, v72, v71, s75 bitop3:0x36
	v_mfma_f32_32x32x16_bf16 a[96:111], v[220:223], v[204:207], a[96:111]
	v_accvgpr_read_b32 v72, a184
	v_ashrrev_i32_e32 v73, 31, v72
	v_bitop3_b32 v72, v73, v72, s75 bitop3:0x36
	v_accvgpr_read_b32 v73, a185
	v_ashrrev_i32_e32 v74, 31, v73
	v_bitop3_b32 v73, v74, v73, s75 bitop3:0x36
	v_accvgpr_read_b32 v74, a186
	v_mfma_f32_32x32x16_bf16 a[112:127], v[216:219], v[204:207], a[112:127]
	v_and_or_b32 v205, v182, s33, v181
	v_accvgpr_read_b32 v182, a129
	v_ashrrev_i32_e32 v183, 31, v182
	v_bitop3_b32 v183, v183, v182, s75 bitop3:0x36
	v_xor_b32_e32 v182, 30, v196
	v_and_or_b32 v206, v183, s33, v182
	v_accvgpr_read_b32 v183, a130
	v_mfma_f32_32x32x16_bf16 a[16:31], v[184:187], v[188:191], a[16:31]
	v_ashrrev_i32_e32 v184, 31, v183
	v_bitop3_b32 v184, v184, v183, s75 bitop3:0x36
	v_xor_b32_e32 v183, 29, v196
	v_and_or_b32 v207, v184, s33, v183
	v_accvgpr_read_b32 v184, a131
	v_ashrrev_i32_e32 v185, 31, v184
	v_bitop3_b32 v185, v185, v184, s75 bitop3:0x36
	v_xor_b32_e32 v184, 28, v196
	v_mfma_f32_32x32x16_bf16 a[16:31], v[208:211], v[212:215], a[16:31]
	v_and_or_b32 v208, v185, s33, v184
	v_accvgpr_read_b32 v185, a132
	v_ashrrev_i32_e32 v186, 31, v185
	v_bitop3_b32 v186, v186, v185, s75 bitop3:0x36
	v_xor_b32_e32 v185, 23, v196
	v_and_or_b32 v209, v186, s33, v185
	v_accvgpr_read_b32 v186, a133
	v_mfma_f32_32x32x16_bf16 a[48:63], v[192:195], v[188:191], a[48:63]
	v_ashrrev_i32_e32 v187, 31, v186
	v_bitop3_b32 v187, v187, v186, s75 bitop3:0x36
	v_xor_b32_e32 v186, 22, v196
	v_and_or_b32 v210, v187, s33, v186
	v_accvgpr_read_b32 v187, a134
	v_ashrrev_i32_e32 v188, 31, v187
	v_bitop3_b32 v188, v188, v187, s75 bitop3:0x36
	v_xor_b32_e32 v187, 21, v196
	v_and_or_b32 v211, v188, s33, v187
	v_accvgpr_read_b32 v188, a135
	v_ashrrev_i32_e32 v189, 31, v188
	v_bitop3_b32 v189, v189, v188, s75 bitop3:0x36
	v_xor_b32_e32 v188, 20, v196
	v_mfma_f32_32x32x16_bf16 a[0:15], v[200:203], v[212:215], a[0:15]
	v_ashrrev_i32_e32 v75, 31, v74
	v_bitop3_b32 v74, v75, v74, s75 bitop3:0x36
	v_accvgpr_read_b32 v75, a187
	v_accvgpr_read_b32 v99, a171
	v_ashrrev_i32_e32 v76, 31, v75
	v_ashrrev_i32_e32 v100, 31, v99
	v_bitop3_b32 v75, v76, v75, s75 bitop3:0x36
	v_mfma_f32_32x32x16_bf16 a[32:47], v[220:223], v[212:215], a[32:47]
	v_accvgpr_read_b32 v76, a188
	v_bitop3_b32 v99, v100, v99, s75 bitop3:0x36
	v_accvgpr_read_b32 v100, a172
	v_ashrrev_i32_e32 v77, 31, v76
	v_ashrrev_i32_e32 v101, 31, v100
	v_bitop3_b32 v76, v77, v76, s75 bitop3:0x36
	v_accvgpr_read_b32 v77, a189
	v_mfma_f32_32x32x16_bf16 a[48:63], v[216:219], v[212:215], a[48:63]
	v_and_or_b32 v212, v189, s33, v188
	v_accvgpr_read_b32 v189, a136
	v_ashrrev_i32_e32 v190, 31, v189
	v_bitop3_b32 v190, v190, v189, s75 bitop3:0x36
	v_xor_b32_e32 v189, 15, v196
	v_and_or_b32 v213, v190, s33, v189
	v_accvgpr_read_b32 v190, a137
	v_ashrrev_i32_e32 v191, 31, v190
	v_bitop3_b32 v191, v191, v190, s75 bitop3:0x36
	v_xor_b32_e32 v190, 14, v196
	v_and_or_b32 v214, v191, s33, v190
	v_accvgpr_read_b32 v191, a138
	v_ashrrev_i32_e32 v192, 31, v191
	v_bitop3_b32 v192, v192, v191, s75 bitop3:0x36
	v_xor_b32_e32 v191, 13, v196
	v_and_or_b32 v215, v192, s33, v191
	v_accvgpr_read_b32 v192, a139
	v_ashrrev_i32_e32 v193, 31, v192
	v_bitop3_b32 v193, v193, v192, s75 bitop3:0x36
	v_xor_b32_e32 v192, 12, v196
	v_and_or_b32 v216, v193, s33, v192
	v_accvgpr_read_b32 v193, a140
	v_ashrrev_i32_e32 v194, 31, v193
	v_bitop3_b32 v100, v101, v100, s75 bitop3:0x36
	v_accvgpr_read_b32 v101, a173
	v_bitop3_b32 v194, v194, v193, s75 bitop3:0x36
	v_xor_b32_e32 v193, 7, v196
	v_ashrrev_i32_e32 v78, 31, v77
	v_ashrrev_i32_e32 v102, 31, v101
	v_and_or_b32 v217, v194, s33, v193
	v_accvgpr_read_b32 v194, a141
	v_bitop3_b32 v77, v78, v77, s75 bitop3:0x36
	v_accvgpr_read_b32 v78, a190
	v_bitop3_b32 v101, v102, v101, s75 bitop3:0x36
	v_accvgpr_read_b32 v102, a174
	v_ashrrev_i32_e32 v195, 31, v194
	v_ashrrev_i32_e32 v79, 31, v78
	v_ashrrev_i32_e32 v103, 31, v102
	v_bitop3_b32 v195, v195, v194, s75 bitop3:0x36
	v_xor_b32_e32 v194, 6, v196
	v_bitop3_b32 v78, v79, v78, s75 bitop3:0x36
	v_accvgpr_read_b32 v79, a191
	v_bitop3_b32 v102, v103, v102, s75 bitop3:0x36
	v_accvgpr_read_b32 v103, a175
	v_and_or_b32 v218, v195, s33, v194
	v_accvgpr_read_b32 v195, a142
	v_accvgpr_read_b32 v220, a143
	v_ashrrev_i32_e32 v80, 31, v79
	v_ashrrev_i32_e32 v104, 31, v103
	v_ashrrev_i32_e32 v219, 31, v195
	v_ashrrev_i32_e32 v221, 31, v220
	v_xor_b32_e32 v136, 0x7c, v196
	v_xor_b32_e32 v137, 0x77, v196
	v_xor_b32_e32 v138, 0x76, v196
	v_xor_b32_e32 v139, 0x75, v196
	v_xor_b32_e32 v141, 0x74, v196
	v_xor_b32_e32 v140, 0x6f, v196
	v_xor_b32_e32 v142, 0x6e, v196
	v_xor_b32_e32 v143, 0x6d, v196
	v_xor_b32_e32 v144, 0x6c, v196
	v_xor_b32_e32 v145, 0x67, v196
	v_xor_b32_e32 v146, 0x66, v196
	v_bitop3_b32 v79, v80, v79, s75 bitop3:0x36
	v_xor_b32_e32 v147, 0x64, v196
	v_xor_b32_e32 v152, 0x5c, v196
	v_xor_b32_e32 v153, 0x57, v196
	v_xor_b32_e32 v154, 0x56, v196
	v_xor_b32_e32 v155, 0x55, v196
	v_xor_b32_e32 v156, 0x54, v196
	v_xor_b32_e32 v157, 0x4f, v196
	v_xor_b32_e32 v158, 0x4e, v196
	v_xor_b32_e32 v159, 0x4d, v196
	v_xor_b32_e32 v160, 0x4c, v196
	v_xor_b32_e32 v161, 0x47, v196
	v_xor_b32_e32 v162, 0x46, v196
	v_xor_b32_e32 v163, 0x45, v196
	v_bitop3_b32 v103, v104, v103, s75 bitop3:0x36
	v_xor_b32_e32 v164, 0x44, v196
	v_bitop3_b32 v219, v219, v195, s75 bitop3:0x36
	v_xor_b32_e32 v195, 5, v196
	v_bitop3_b32 v220, v221, v220, s75 bitop3:0x36
	v_xor_b32_e32 v196, 4, v196
	v_and_or_b32 v64, v64, s33, v129
	v_and_or_b32 v65, v65, s33, v134
	v_and_or_b32 v66, v66, s33, v135
	v_and_or_b32 v67, v67, s33, v136
	v_and_or_b32 v68, v68, s33, v137
	v_and_or_b32 v69, v69, s33, v138
	v_and_or_b32 v70, v70, s33, v139
	v_and_or_b32 v71, v71, s33, v141
	v_and_or_b32 v72, v72, s33, v140
	v_and_or_b32 v73, v73, s33, v142
	v_and_or_b32 v74, v74, s33, v143
	v_and_or_b32 v75, v75, s33, v144
	v_and_or_b32 v76, v76, s33, v145
	v_and_or_b32 v77, v77, s33, v146
	v_and_or_b32 v78, v78, s33, v148
	v_and_or_b32 v79, v79, s33, v147
	v_and_or_b32 v88, v88, s33, v149
	v_and_or_b32 v89, v89, s33, v150
	v_and_or_b32 v90, v90, s33, v151
	v_and_or_b32 v91, v91, s33, v152
	v_and_or_b32 v92, v92, s33, v153
	v_and_or_b32 v93, v93, s33, v154
	v_and_or_b32 v94, v94, s33, v155
	v_and_or_b32 v95, v95, s33, v156
	v_and_or_b32 v96, v96, s33, v157
	v_and_or_b32 v97, v97, s33, v158
	v_and_or_b32 v98, v98, s33, v159
	v_and_or_b32 v99, v99, s33, v160
	v_and_or_b32 v100, v100, s33, v161
	v_and_or_b32 v101, v101, s33, v162
	v_and_or_b32 v102, v102, s33, v163
	v_and_or_b32 v103, v103, s33, v164
	v_and_or_b32 v219, v219, s33, v195
	v_and_or_b32 v220, v220, s33, v196
	v_max_u32_e32 v80, v64, v65
	v_min_u32_e32 v64, v64, v65
	v_max_u32_e32 v65, v66, v67
	v_min_u32_e32 v66, v66, v67
	v_max_u32_e32 v67, v68, v69
	v_min_u32_e32 v68, v68, v69
	v_max_u32_e32 v69, v70, v71
	v_min_u32_e32 v70, v70, v71
	v_max_u32_e32 v71, v72, v73
	v_min_u32_e32 v72, v72, v73
	v_max_u32_e32 v73, v74, v75
	v_min_u32_e32 v74, v74, v75
	v_max_u32_e32 v75, v76, v77
	v_min_u32_e32 v76, v76, v77
	v_max_u32_e32 v77, v78, v79
	v_min_u32_e32 v78, v78, v79
	v_max_u32_e32 v104, v88, v89
	v_min_u32_e32 v88, v88, v89
	v_max_u32_e32 v89, v90, v91
	v_min_u32_e32 v90, v90, v91
	v_max_u32_e32 v91, v92, v93
	v_min_u32_e32 v92, v92, v93
	v_max_u32_e32 v93, v94, v95
	v_min_u32_e32 v94, v94, v95
	v_max_u32_e32 v95, v96, v97
	v_min_u32_e32 v96, v96, v97
	v_max_u32_e32 v97, v98, v99
	v_min_u32_e32 v98, v98, v99
	v_max_u32_e32 v99, v100, v101
	v_min_u32_e32 v100, v100, v101
	v_max_u32_e32 v101, v102, v103
	v_min_u32_e32 v102, v102, v103
	v_max_u32_e32 v221, v205, v206
	v_min_u32_e32 v205, v205, v206
	v_max_u32_e32 v206, v207, v208
	v_min_u32_e32 v207, v207, v208
	v_max_u32_e32 v208, v209, v210
	v_min_u32_e32 v209, v209, v210
	v_max_u32_e32 v210, v211, v212
	v_min_u32_e32 v211, v211, v212
	v_max_u32_e32 v212, v213, v214
	v_min_u32_e32 v213, v213, v214
	v_max_u32_e32 v214, v215, v216
	v_min_u32_e32 v215, v215, v216
	v_max_u32_e32 v216, v217, v218
	v_min_u32_e32 v217, v217, v218
	v_max_u32_e32 v218, v219, v220
	v_min_u32_e32 v219, v219, v220
	v_max_u32_e32 v79, v80, v66
	v_min_u32_e32 v66, v80, v66
	v_max_u32_e32 v80, v64, v65
	v_min_u32_e32 v64, v64, v65
	v_max_u32_e32 v65, v67, v70
	v_min_u32_e32 v67, v67, v70
	v_max_u32_e32 v70, v68, v69
	v_min_u32_e32 v68, v68, v69
	v_max_u32_e32 v69, v71, v74
	v_min_u32_e32 v71, v71, v74
	v_max_u32_e32 v74, v72, v73
	v_min_u32_e32 v72, v72, v73
	v_max_u32_e32 v73, v75, v78
	v_min_u32_e32 v75, v75, v78
	v_max_u32_e32 v78, v76, v77
	v_min_u32_e32 v76, v76, v77
	v_max_u32_e32 v103, v104, v90
	v_min_u32_e32 v90, v104, v90
	v_max_u32_e32 v104, v88, v89
	v_min_u32_e32 v88, v88, v89
	v_max_u32_e32 v89, v91, v94
	v_min_u32_e32 v91, v91, v94
	v_max_u32_e32 v94, v92, v93
	v_min_u32_e32 v92, v92, v93
	v_max_u32_e32 v93, v95, v98
	v_min_u32_e32 v95, v95, v98
	v_max_u32_e32 v98, v96, v97
	v_min_u32_e32 v96, v96, v97
	v_max_u32_e32 v97, v99, v102
	v_min_u32_e32 v99, v99, v102
	v_max_u32_e32 v102, v100, v101
	v_min_u32_e32 v100, v100, v101
	v_max_u32_e32 v220, v221, v207
	v_min_u32_e32 v207, v221, v207
	v_max_u32_e32 v221, v205, v206
	v_min_u32_e32 v205, v205, v206
	v_max_u32_e32 v206, v208, v211
	v_min_u32_e32 v208, v208, v211
	v_max_u32_e32 v211, v209, v210
	v_min_u32_e32 v209, v209, v210
	v_max_u32_e32 v210, v212, v215
	v_min_u32_e32 v212, v212, v215
	v_max_u32_e32 v215, v213, v214
	v_min_u32_e32 v213, v213, v214
	v_max_u32_e32 v214, v216, v219
	v_min_u32_e32 v216, v216, v219
	v_max_u32_e32 v219, v217, v218
	v_min_u32_e32 v217, v217, v218
	v_max_u32_e32 v77, v79, v80
	v_min_u32_e32 v79, v79, v80
	v_max_u32_e32 v80, v66, v64
	v_min_u32_e32 v64, v66, v64
	v_max_u32_e32 v66, v67, v68
	v_min_u32_e32 v67, v67, v68
	v_max_u32_e32 v68, v65, v70
	v_min_u32_e32 v65, v65, v70
	v_max_u32_e32 v70, v69, v74
	v_min_u32_e32 v69, v69, v74
	v_max_u32_e32 v74, v71, v72
	v_min_u32_e32 v71, v71, v72
	v_max_u32_e32 v72, v75, v76
	v_min_u32_e32 v75, v75, v76
	v_max_u32_e32 v76, v73, v78
	v_min_u32_e32 v73, v73, v78
	v_max_u32_e32 v101, v103, v104
	v_min_u32_e32 v103, v103, v104
	v_max_u32_e32 v104, v90, v88
	v_min_u32_e32 v88, v90, v88
	v_max_u32_e32 v90, v91, v92
	v_min_u32_e32 v91, v91, v92
	v_max_u32_e32 v92, v89, v94
	v_min_u32_e32 v89, v89, v94
	v_max_u32_e32 v94, v93, v98
	v_min_u32_e32 v93, v93, v98
	v_max_u32_e32 v98, v95, v96
	v_min_u32_e32 v95, v95, v96
	v_max_u32_e32 v96, v99, v100
	v_min_u32_e32 v99, v99, v100
	v_max_u32_e32 v100, v97, v102
	v_min_u32_e32 v97, v97, v102
	v_max_u32_e32 v218, v220, v221
	v_min_u32_e32 v220, v220, v221
	v_max_u32_e32 v221, v207, v205
	v_min_u32_e32 v205, v207, v205
	v_max_u32_e32 v207, v208, v209
	v_min_u32_e32 v208, v208, v209
	v_max_u32_e32 v209, v206, v211
	v_min_u32_e32 v206, v206, v211
	v_max_u32_e32 v211, v210, v215
	v_min_u32_e32 v210, v210, v215
	v_max_u32_e32 v215, v212, v213
	v_min_u32_e32 v212, v212, v213
	v_max_u32_e32 v213, v216, v217
	v_min_u32_e32 v216, v216, v217
	v_max_u32_e32 v217, v214, v219
	v_min_u32_e32 v214, v214, v219
	v_max_u32_e32 v78, v77, v67
	v_min_u32_e32 v67, v77, v67
	v_max_u32_e32 v77, v79, v66
	v_min_u32_e32 v66, v79, v66
	v_max_u32_e32 v79, v80, v65
	v_min_u32_e32 v65, v80, v65
	v_max_u32_e32 v80, v64, v68
	v_min_u32_e32 v64, v64, v68
	v_max_u32_e32 v68, v70, v75
	v_min_u32_e32 v70, v70, v75
	v_max_u32_e32 v75, v69, v72
	v_min_u32_e32 v69, v69, v72
	v_max_u32_e32 v72, v74, v73
	v_min_u32_e32 v73, v74, v73
	v_max_u32_e32 v74, v71, v76
	v_min_u32_e32 v71, v71, v76
	v_max_u32_e32 v102, v101, v91
	v_min_u32_e32 v91, v101, v91
	v_max_u32_e32 v101, v103, v90
	v_min_u32_e32 v90, v103, v90
	v_max_u32_e32 v103, v104, v89
	v_min_u32_e32 v89, v104, v89
	v_max_u32_e32 v104, v88, v92
	v_min_u32_e32 v88, v88, v92
	v_max_u32_e32 v92, v94, v99
	v_min_u32_e32 v94, v94, v99
	v_max_u32_e32 v99, v93, v96
	v_min_u32_e32 v93, v93, v96
	v_max_u32_e32 v96, v98, v97
	v_min_u32_e32 v97, v98, v97
	v_max_u32_e32 v98, v95, v100
	v_min_u32_e32 v95, v95, v100
	v_max_u32_e32 v219, v218, v208
	v_min_u32_e32 v208, v218, v208
	v_max_u32_e32 v218, v220, v207
	v_min_u32_e32 v207, v220, v207
	v_max_u32_e32 v220, v221, v206
	v_min_u32_e32 v206, v221, v206
	v_max_u32_e32 v221, v205, v209
	v_min_u32_e32 v205, v205, v209
	v_max_u32_e32 v209, v211, v216
	v_min_u32_e32 v211, v211, v216
	v_max_u32_e32 v216, v210, v213
	v_min_u32_e32 v210, v210, v213
	v_max_u32_e32 v213, v215, v214
	v_min_u32_e32 v214, v215, v214
	v_max_u32_e32 v215, v212, v217
	v_min_u32_e32 v212, v212, v217
	v_max_u32_e32 v76, v78, v79
	v_min_u32_e32 v78, v78, v79
	v_max_u32_e32 v79, v77, v80
	v_min_u32_e32 v77, v77, v80
	v_max_u32_e32 v80, v67, v65
	v_min_u32_e32 v65, v67, v65
	v_max_u32_e32 v67, v66, v64
	v_min_u32_e32 v64, v66, v64
	v_max_u32_e32 v66, v70, v73
	v_min_u32_e32 v70, v70, v73
	v_max_u32_e32 v73, v69, v71
	v_min_u32_e32 v69, v69, v71
	v_max_u32_e32 v71, v68, v72
	v_min_u32_e32 v68, v68, v72
	v_max_u32_e32 v72, v75, v74
	v_min_u32_e32 v74, v75, v74
	v_max_u32_e32 v100, v102, v103
	v_min_u32_e32 v102, v102, v103
	v_max_u32_e32 v103, v101, v104
	v_min_u32_e32 v101, v101, v104
	v_max_u32_e32 v104, v91, v89
	v_min_u32_e32 v89, v91, v89
	v_max_u32_e32 v91, v90, v88
	v_min_u32_e32 v88, v90, v88
	v_max_u32_e32 v90, v94, v97
	v_min_u32_e32 v94, v94, v97
	v_max_u32_e32 v97, v93, v95
	v_min_u32_e32 v93, v93, v95
	v_max_u32_e32 v95, v92, v96
	v_min_u32_e32 v92, v92, v96
	v_max_u32_e32 v96, v99, v98
	v_min_u32_e32 v98, v99, v98
	v_max_u32_e32 v217, v219, v220
	v_min_u32_e32 v219, v219, v220
	v_max_u32_e32 v220, v218, v221
	v_min_u32_e32 v218, v218, v221
	v_max_u32_e32 v221, v208, v206
	v_min_u32_e32 v206, v208, v206
	v_max_u32_e32 v208, v207, v205
	v_min_u32_e32 v205, v207, v205
	v_max_u32_e32 v207, v211, v214
	v_min_u32_e32 v211, v211, v214
	v_max_u32_e32 v214, v210, v212
	v_min_u32_e32 v210, v210, v212
	v_max_u32_e32 v212, v209, v213
	v_min_u32_e32 v209, v209, v213
	v_max_u32_e32 v213, v216, v215
	v_min_u32_e32 v215, v216, v215
	v_max_u32_e32 v75, v76, v79
	v_min_u32_e32 v76, v76, v79
	v_max_u32_e32 v79, v78, v77
	v_min_u32_e32 v77, v78, v77
	v_max_u32_e32 v78, v80, v67
	v_min_u32_e32 v67, v80, v67
	v_max_u32_e32 v80, v65, v64
	v_min_u32_e32 v64, v65, v64
	v_max_u32_e32 v65, v70, v69
	v_min_u32_e32 v69, v70, v69
	v_max_u32_e32 v70, v66, v73
	v_min_u32_e32 v66, v66, v73
	v_max_u32_e32 v73, v68, v74
	v_min_u32_e32 v68, v68, v74
	v_max_u32_e32 v74, v71, v72
	v_min_u32_e32 v71, v71, v72
	v_max_u32_e32 v99, v100, v103
	v_min_u32_e32 v100, v100, v103
	v_max_u32_e32 v103, v102, v101
	v_min_u32_e32 v101, v102, v101
	v_max_u32_e32 v102, v104, v91
	v_min_u32_e32 v91, v104, v91
	v_max_u32_e32 v104, v89, v88
	v_min_u32_e32 v88, v89, v88
	v_max_u32_e32 v89, v94, v93
	v_min_u32_e32 v93, v94, v93
	v_max_u32_e32 v94, v90, v97
	v_min_u32_e32 v90, v90, v97
	v_max_u32_e32 v97, v92, v98
	v_min_u32_e32 v92, v92, v98
	v_max_u32_e32 v98, v95, v96
	v_min_u32_e32 v95, v95, v96
	v_max_u32_e32 v216, v217, v220
	v_min_u32_e32 v217, v217, v220
	v_max_u32_e32 v220, v219, v218
	v_min_u32_e32 v218, v219, v218
	v_max_u32_e32 v219, v221, v208
	v_min_u32_e32 v208, v221, v208
	v_max_u32_e32 v221, v206, v205
	v_min_u32_e32 v205, v206, v205
	v_max_u32_e32 v206, v211, v210
	v_min_u32_e32 v210, v211, v210
	v_max_u32_e32 v211, v207, v214
	v_min_u32_e32 v207, v207, v214
	v_max_u32_e32 v214, v209, v215
	v_min_u32_e32 v209, v209, v215
	v_max_u32_e32 v215, v212, v213
	v_min_u32_e32 v212, v212, v213
	v_max_u32_e32 v72, v75, v69
	v_min_u32_e32 v69, v75, v69
	v_max_u32_e32 v75, v76, v65
	v_min_u32_e32 v65, v76, v65
	v_max_u32_e32 v76, v79, v66
	v_min_u32_e32 v66, v79, v66
	v_max_u32_e32 v79, v77, v70
	v_min_u32_e32 v70, v77, v70
	v_max_u32_e32 v77, v78, v68
	v_min_u32_e32 v68, v78, v68
	v_max_u32_e32 v78, v67, v73
	v_min_u32_e32 v67, v67, v73
	v_max_u32_e32 v73, v80, v71
	v_min_u32_e32 v71, v80, v71
	v_max_u32_e32 v80, v64, v74
	v_min_u32_e32 v64, v64, v74
	v_max_u32_e32 v96, v99, v93
	v_min_u32_e32 v93, v99, v93
	v_max_u32_e32 v99, v100, v89
	v_min_u32_e32 v89, v100, v89
	v_max_u32_e32 v100, v103, v90
	v_min_u32_e32 v90, v103, v90
	v_max_u32_e32 v103, v101, v94
	v_min_u32_e32 v94, v101, v94
	v_max_u32_e32 v101, v102, v92
	v_min_u32_e32 v92, v102, v92
	v_max_u32_e32 v102, v91, v97
	v_min_u32_e32 v91, v91, v97
	v_max_u32_e32 v97, v104, v95
	v_min_u32_e32 v95, v104, v95
	v_max_u32_e32 v104, v88, v98
	v_min_u32_e32 v88, v88, v98
	v_max_u32_e32 v213, v216, v210
	v_min_u32_e32 v210, v216, v210
	v_max_u32_e32 v216, v217, v206
	v_min_u32_e32 v206, v217, v206
	v_max_u32_e32 v217, v220, v207
	v_min_u32_e32 v207, v220, v207
	v_max_u32_e32 v220, v218, v211
	v_min_u32_e32 v211, v218, v211
	v_max_u32_e32 v218, v219, v209
	v_min_u32_e32 v209, v219, v209
	v_max_u32_e32 v219, v208, v214
	v_min_u32_e32 v208, v208, v214
	v_max_u32_e32 v214, v221, v212
	v_min_u32_e32 v212, v221, v212
	v_max_u32_e32 v221, v205, v215
	v_min_u32_e32 v205, v205, v215
	v_max_u32_e32 v74, v72, v77
	v_min_u32_e32 v72, v72, v77
	v_max_u32_e32 v77, v75, v78
	v_min_u32_e32 v75, v75, v78
	v_max_u32_e32 v78, v76, v73
	v_min_u32_e32 v73, v76, v73
	v_max_u32_e32 v76, v79, v80
	v_min_u32_e32 v79, v79, v80
	v_max_u32_e32 v80, v69, v68
	v_min_u32_e32 v81, v69, v68
	v_max_u32_e32 v82, v65, v67
	v_min_u32_e32 v83, v65, v67
	v_max_u32_e32 v84, v66, v71
	v_min_u32_e32 v85, v66, v71
	v_max_u32_e32 v86, v70, v64
	v_min_u32_e32 v87, v70, v64
	v_max_u32_e32 v98, v96, v101
	v_min_u32_e32 v96, v96, v101
	v_max_u32_e32 v101, v99, v102
	v_min_u32_e32 v99, v99, v102
	v_max_u32_e32 v102, v100, v97
	v_min_u32_e32 v97, v100, v97
	v_max_u32_e32 v100, v103, v104
	v_min_u32_e32 v103, v103, v104
	v_max_u32_e32 v104, v93, v92
	v_min_u32_e32 v92, v93, v92
	v_max_u32_e32 v93, v89, v91
	v_min_u32_e32 v89, v89, v91
	v_max_u32_e32 v91, v90, v95
	v_min_u32_e32 v90, v90, v95
	v_max_u32_e32 v95, v94, v88
	v_min_u32_e32 v88, v94, v88
	v_max_u32_e32 v215, v213, v218
	v_min_u32_e32 v213, v213, v218
	v_max_u32_e32 v218, v216, v219
	v_min_u32_e32 v216, v216, v219
	v_max_u32_e32 v219, v217, v214
	v_min_u32_e32 v214, v217, v214
	v_max_u32_e32 v217, v220, v221
	v_min_u32_e32 v220, v220, v221
	v_max_u32_e32 v221, v210, v209
	v_min_u32_e32 v209, v210, v209
	v_max_u32_e32 v210, v206, v208
	v_min_u32_e32 v206, v206, v208
	v_max_u32_e32 v208, v207, v212
	v_min_u32_e32 v207, v207, v212
	v_max_u32_e32 v212, v211, v205
	v_min_u32_e32 v205, v211, v205
	v_max_u32_e32 v65, v74, v78
	v_min_u32_e32 v64, v74, v78
	v_max_u32_e32 v67, v77, v76
	v_min_u32_e32 v68, v77, v76
	v_max_u32_e32 v66, v72, v73
	v_min_u32_e32 v69, v72, v73
	v_max_u32_e32 v73, v75, v79
	v_min_u32_e32 v72, v75, v79
	v_max_u32_e32 v71, v80, v84
	v_min_u32_e32 v70, v80, v84
	v_max_u32_e32 v76, v82, v86
	v_min_u32_e32 v74, v82, v86
	v_max_u32_e32 v77, v81, v85
	v_min_u32_e32 v75, v81, v85
	v_max_u32_e32 v79, v83, v87
	v_min_u32_e32 v78, v83, v87
	v_max_u32_e32 v94, v98, v102
	v_min_u32_e32 v98, v98, v102
	v_max_u32_e32 v102, v101, v100
	v_min_u32_e32 v100, v101, v100
	v_max_u32_e32 v101, v96, v97
	v_min_u32_e32 v96, v96, v97
	v_max_u32_e32 v97, v99, v103
	v_min_u32_e32 v99, v99, v103
	v_max_u32_e32 v103, v104, v91
	v_min_u32_e32 v91, v104, v91
	v_max_u32_e32 v104, v93, v95
	v_min_u32_e32 v93, v93, v95
	v_max_u32_e32 v95, v92, v90
	v_min_u32_e32 v90, v92, v90
	v_max_u32_e32 v92, v89, v88
	v_min_u32_e32 v88, v89, v88
	v_max_u32_e32 v197, v117, v119
	v_min_u32_e32 v117, v117, v119
	v_max_u32_e32 v119, v116, v114
	v_min_u32_e32 v114, v116, v114
	v_max_u32_e32 v116, v113, v112
	v_min_u32_e32 v112, v113, v112
	v_max_u32_e32 v211, v215, v219
	v_min_u32_e32 v215, v215, v219
	v_max_u32_e32 v219, v218, v217
	v_min_u32_e32 v217, v218, v217
	v_max_u32_e32 v218, v213, v214
	v_min_u32_e32 v213, v213, v214
	v_max_u32_e32 v214, v216, v220
	v_min_u32_e32 v216, v216, v220
	v_max_u32_e32 v220, v221, v208
	v_min_u32_e32 v208, v221, v208
	v_max_u32_e32 v221, v210, v212
	v_min_u32_e32 v210, v210, v212
	v_max_u32_e32 v212, v209, v207
	v_min_u32_e32 v207, v209, v207
	v_max_u32_e32 v209, v206, v205
	v_min_u32_e32 v205, v206, v205
	v_min_u32_e32 v85, v65, v67
	v_min_u32_e32 v86, v64, v68
	v_min_u32_e32 v83, v66, v73
	v_min_u32_e32 v87, v69, v72
	v_min_u32_e32 v84, v71, v76
	v_min_u32_e32 v82, v70, v74
	v_min_u32_e32 v81, v77, v79
	v_min_u32_e32 v80, v75, v78
	v_min_u32_e32 v89, v94, v102
	v_min_u32_e32 v105, v98, v100
	v_min_u32_e32 v106, v101, v97
	v_min_u32_e32 v107, v96, v99
	v_min_u32_e32 v108, v103, v104
	v_min_u32_e32 v109, v91, v93
	v_min_u32_e32 v110, v95, v92
	v_min_u32_e32 v111, v90, v88
	v_min_u32_e32 v113, v118, v126
	v_min_u32_e32 v198, v122, v124
	v_min_u32_e32 v199, v125, v121
	v_min_u32_e32 v200, v120, v123
	v_min_u32_e32 v201, v127, v197
	v_min_u32_e32 v202, v115, v117
	v_min_u32_e32 v203, v119, v116
	v_min_u32_e32 v204, v114, v112
	v_min_u32_e32 v206, v211, v219
	v_min_u32_e32 v222, v215, v217
	v_min_u32_e32 v223, v218, v214
	v_min_u32_e32 v224, v213, v216
	v_min_u32_e32 v225, v220, v221
	v_min_u32_e32 v226, v208, v210
	v_min_u32_e32 v227, v212, v209
	v_min_u32_e32 v228, v207, v205
	v_max3_u32 v65, v65, v67, v111
	v_max3_u32 v67, v85, v90, v88
	v_max3_u32 v64, v64, v68, v110
	v_max3_u32 v68, v86, v95, v92
	v_max3_u32 v66, v66, v73, v109
	v_max3_u32 v73, v83, v91, v93
	v_max3_u32 v69, v69, v72, v108
	v_max3_u32 v72, v87, v103, v104
	v_max3_u32 v71, v71, v76, v107
	v_max3_u32 v76, v84, v96, v99
	v_max3_u32 v70, v70, v74, v106
	v_max3_u32 v74, v82, v101, v97
	v_max3_u32 v77, v77, v79, v105
	v_max3_u32 v79, v81, v98, v100
	v_max3_u32 v75, v75, v78, v89
	v_max3_u32 v78, v80, v94, v102
	v_max3_u32 v88, v118, v126, v228
	v_max3_u32 v89, v113, v207, v205
	v_max3_u32 v90, v122, v124, v227
	v_max3_u32 v91, v198, v212, v209
	v_max3_u32 v92, v125, v121, v226
	v_max3_u32 v93, v199, v208, v210
	v_max3_u32 v94, v120, v123, v225
	v_max3_u32 v95, v200, v220, v221
	v_max3_u32 v96, v127, v197, v224
	v_max3_u32 v97, v201, v213, v216
	v_max3_u32 v98, v115, v117, v223
	v_max3_u32 v99, v202, v218, v214
	v_max3_u32 v100, v119, v116, v222
	v_max3_u32 v101, v203, v215, v217
	v_max3_u32 v102, v114, v112, v206
	v_max3_u32 v103, v204, v211, v219
	v_max_u32_e32 v80, v65, v71
	v_min_u32_e32 v65, v65, v71
	v_max_u32_e32 v71, v67, v76
	v_min_u32_e32 v67, v67, v76
	v_max_u32_e32 v76, v64, v70
	v_min_u32_e32 v64, v64, v70
	v_max_u32_e32 v70, v68, v74
	v_min_u32_e32 v68, v68, v74
	v_max_u32_e32 v74, v66, v77
	v_min_u32_e32 v66, v66, v77
	v_max_u32_e32 v77, v73, v79
	v_min_u32_e32 v73, v73, v79
	v_max_u32_e32 v79, v69, v75
	v_min_u32_e32 v69, v69, v75
	v_max_u32_e32 v75, v72, v78
	v_min_u32_e32 v72, v72, v78
	v_max_u32_e32 v104, v88, v96
	v_min_u32_e32 v88, v88, v96
	v_max_u32_e32 v96, v89, v97
	v_min_u32_e32 v89, v89, v97
	v_max_u32_e32 v97, v90, v98
	v_min_u32_e32 v90, v90, v98
	v_max_u32_e32 v98, v91, v99
	v_min_u32_e32 v91, v91, v99
	v_max_u32_e32 v99, v92, v100
	v_min_u32_e32 v92, v92, v100
	v_max_u32_e32 v100, v93, v101
	v_min_u32_e32 v93, v93, v101
	v_max_u32_e32 v101, v94, v102
	v_min_u32_e32 v94, v94, v102
	v_max_u32_e32 v102, v95, v103
	v_min_u32_e32 v95, v95, v103
	v_max_u32_e32 v78, v80, v74
	v_min_u32_e32 v74, v80, v74
	v_max_u32_e32 v80, v71, v77
	v_min_u32_e32 v71, v71, v77
	v_max_u32_e32 v77, v76, v79
	v_min_u32_e32 v76, v76, v79
	v_max_u32_e32 v79, v70, v75
	v_min_u32_e32 v70, v70, v75
	v_max_u32_e32 v75, v65, v66
	v_min_u32_e32 v65, v65, v66
	v_max_u32_e32 v66, v67, v73
	v_min_u32_e32 v67, v67, v73
	v_max_u32_e32 v73, v64, v69
	v_min_u32_e32 v64, v64, v69
	v_max_u32_e32 v69, v68, v72
	v_min_u32_e32 v68, v68, v72
	v_max_u32_e32 v103, v104, v99
	v_min_u32_e32 v99, v104, v99
	v_max_u32_e32 v104, v96, v100
	v_min_u32_e32 v96, v96, v100
	v_max_u32_e32 v100, v97, v101
	v_min_u32_e32 v97, v97, v101
	v_max_u32_e32 v101, v98, v102
	v_min_u32_e32 v98, v98, v102
	v_max_u32_e32 v102, v88, v92
	v_min_u32_e32 v88, v88, v92
	v_max_u32_e32 v92, v89, v93
	v_min_u32_e32 v89, v89, v93
	v_max_u32_e32 v93, v90, v94
	v_min_u32_e32 v90, v90, v94
	v_max_u32_e32 v94, v91, v95
	v_min_u32_e32 v91, v91, v95
	v_max_u32_e32 v72, v78, v77
	v_min_u32_e32 v77, v78, v77
	v_max_u32_e32 v78, v80, v79
	v_min_u32_e32 v79, v80, v79
	v_max_u32_e32 v80, v74, v76
	v_min_u32_e32 v74, v74, v76
	v_max_u32_e32 v76, v71, v70
	v_min_u32_e32 v70, v71, v70
	v_max_u32_e32 v71, v75, v73
	v_min_u32_e32 v73, v75, v73
	v_max_u32_e32 v75, v66, v69
	v_min_u32_e32 v66, v66, v69
	v_max_u32_e32 v69, v65, v64
	v_min_u32_e32 v64, v65, v64
	v_max_u32_e32 v65, v67, v68
	v_min_u32_e32 v67, v67, v68
	v_max_u32_e32 v95, v103, v100
	v_min_u32_e32 v100, v103, v100
	v_max_u32_e32 v103, v104, v101
	v_min_u32_e32 v101, v104, v101
	v_max_u32_e32 v104, v99, v97
	v_min_u32_e32 v97, v99, v97
	v_max_u32_e32 v99, v96, v98
	v_min_u32_e32 v96, v96, v98
	v_max_u32_e32 v98, v102, v93
	v_min_u32_e32 v93, v102, v93
	v_max_u32_e32 v102, v92, v94
	v_min_u32_e32 v92, v92, v94
	v_max_u32_e32 v94, v88, v90
	v_min_u32_e32 v88, v88, v90
	v_max_u32_e32 v90, v89, v91
	v_min_u32_e32 v89, v89, v91
	v_min_u32_e32 v68, v72, v78
	v_min_u32_e32 v81, v77, v79
	v_min_u32_e32 v82, v80, v76
	v_min_u32_e32 v83, v74, v70
	v_min_u32_e32 v84, v71, v75
	v_min_u32_e32 v85, v73, v66
	v_min_u32_e32 v86, v69, v65
	v_min_u32_e32 v87, v64, v67
	v_min_u32_e32 v91, v95, v103
	v_min_u32_e32 v105, v100, v101
	v_min_u32_e32 v106, v104, v99
	v_min_u32_e32 v107, v97, v96
	v_min_u32_e32 v108, v98, v102
	v_min_u32_e32 v109, v93, v92
	v_min_u32_e32 v110, v94, v90
	v_min_u32_e32 v111, v88, v89
	v_max3_u32 v72, v72, v78, v111
	v_max3_u32 v68, v68, v88, v89
	v_max3_u32 v77, v77, v79, v110
	v_max3_u32 v78, v81, v94, v90
	v_max3_u32 v76, v80, v76, v109
	v_max3_u32 v79, v82, v93, v92
	v_max3_u32 v70, v74, v70, v108
	v_max3_u32 v74, v83, v98, v102
	v_max3_u32 v71, v71, v75, v107
	v_max3_u32 v75, v84, v97, v96
	v_max3_u32 v66, v73, v66, v106
	v_max3_u32 v73, v85, v104, v99
	v_max3_u32 v65, v69, v65, v105
	v_max3_u32 v69, v86, v100, v101
	v_max3_u32 v64, v64, v67, v91
	v_max3_u32 v67, v87, v95, v103
	v_max_u32_e32 v80, v72, v71
	v_min_u32_e32 v71, v72, v71
	v_max_u32_e32 v72, v68, v75
	v_min_u32_e32 v68, v68, v75
	v_max_u32_e32 v75, v77, v66
	v_min_u32_e32 v66, v77, v66
	v_max_u32_e32 v77, v78, v73
	v_min_u32_e32 v73, v78, v73
	v_max_u32_e32 v78, v76, v65
	v_min_u32_e32 v65, v76, v65
	v_max_u32_e32 v76, v79, v69
	v_min_u32_e32 v69, v79, v69
	v_max_u32_e32 v79, v70, v64
	v_min_u32_e32 v64, v70, v64
	v_max_u32_e32 v70, v74, v67
	v_min_u32_e32 v67, v74, v67
	v_max_u32_e32 v74, v80, v78
	v_min_u32_e32 v78, v80, v78
	v_max_u32_e32 v80, v72, v76
	v_min_u32_e32 v72, v72, v76
	v_max_u32_e32 v76, v75, v79
	v_min_u32_e32 v75, v75, v79
	v_max_u32_e32 v79, v77, v70
	v_min_u32_e32 v70, v77, v70
	v_max_u32_e32 v77, v71, v65
	v_min_u32_e32 v65, v71, v65
	v_max_u32_e32 v71, v68, v69
	v_min_u32_e32 v68, v68, v69
	v_max_u32_e32 v69, v66, v64
	v_min_u32_e32 v64, v66, v64
	v_max_u32_e32 v66, v73, v67
	v_min_u32_e32 v67, v73, v67
	v_max_u32_e32 v73, v74, v76
	v_max_u32_e32 v81, v80, v79
	v_min_u32_e32 v79, v80, v79
	v_max_u32_e32 v80, v78, v75
	v_min_u32_e32 v78, v78, v75
	v_max_u32_e32 v82, v72, v70
	v_min_u32_e32 v70, v72, v70
	v_min_u32_e32 v76, v74, v76
	v_max_u32_e32 v83, v77, v69
	v_min_u32_e32 v69, v77, v69
	v_max_u32_e32 v77, v71, v66
	v_min_u32_e32 v71, v71, v66
	v_max_u32_e32 v84, v65, v64
	v_min_u32_e32 v85, v65, v64
	v_max_u32_e32 v74, v73, v81
	v_min_u32_e32 v66, v73, v81
	v_max_u32_e32 v73, v78, v70
	v_min_u32_e32 v65, v78, v70
	v_mbcnt_lo_u32_b32 v78, -1, s4
	v_mbcnt_hi_u32_b32 v78, -1, v78
	v_max_u32_e32 v86, v68, v67
	v_min_u32_e32 v87, v68, v67
	v_lshlrev_b32_e32 v78, 2, v78
	v_max_u32_e32 v72, v76, v79
	v_min_u32_e32 v64, v76, v79
	v_max_u32_e32 v75, v80, v82
	v_min_u32_e32 v67, v80, v82
	v_max_u32_e32 v80, v83, v77
	v_min_u32_e32 v70, v83, v77
	v_max_u32_e32 v76, v69, v71
	v_min_u32_e32 v68, v69, v71
	v_max_u32_e32 v81, v84, v86
	v_min_u32_e32 v71, v84, v86
	v_max_u32_e32 v77, v85, v87
	v_min_u32_e32 v69, v85, v87
	v_xor_b32_e32 v85, 0x80, v78
	ds_bpermute_b32 v90, v85, v69
	ds_bpermute_b32 v82, v85, v77
	ds_bpermute_b32 v88, v85, v71
	ds_bpermute_b32 v78, v85, v81
	ds_bpermute_b32 v91, v85, v68
	ds_bpermute_b32 v83, v85, v76
	ds_bpermute_b32 v89, v85, v70
	ds_bpermute_b32 v79, v85, v80
	ds_bpermute_b32 v94, v85, v65
	ds_bpermute_b32 v86, v85, v73
	ds_bpermute_b32 v92, v85, v67
	ds_bpermute_b32 v84, v85, v75
	ds_bpermute_b32 v95, v85, v64
	ds_bpermute_b32 v87, v85, v72
	ds_bpermute_b32 v93, v85, v66
	ds_bpermute_b32 v85, v85, v74
	s_and_saveexec_b64 s[4:5], vcc
	s_cbranch_execz .LBB0_153
	s_waitcnt lgkmcnt(14)
	v_max_u32_e32 v74, v74, v90
	s_waitcnt lgkmcnt(7)
	v_max_u32_e32 v80, v80, v94
	v_max_u32_e32 v75, v75, v91
	s_waitcnt lgkmcnt(3)
	v_max_u32_e32 v81, v81, v95
	v_max_u32_e32 v72, v72, v88
	v_max_u32_e32 v76, v76, v92
	v_max_u32_e32 v73, v73, v89
	s_waitcnt lgkmcnt(1)
	v_max_u32_e32 v77, v77, v93
	v_max_u32_e32 v82, v66, v82
	v_max_u32_e32 v86, v70, v86
	v_max_u32_e32 v83, v67, v83
	v_max_u32_e32 v87, v71, v87
	v_max_u32_e32 v78, v64, v78
	v_max_u32_e32 v84, v68, v84
	v_max_u32_e32 v79, v65, v79
	s_waitcnt lgkmcnt(0)
	v_max_u32_e32 v85, v69, v85
	v_min_u32_e32 v90, v74, v80
	v_min_u32_e32 v91, v75, v81
	v_min_u32_e32 v88, v72, v76
	v_min_u32_e32 v89, v73, v77
	v_min_u32_e32 v70, v82, v86
	v_min_u32_e32 v71, v83, v87
	v_min_u32_e32 v68, v78, v84
	v_min_u32_e32 v69, v79, v85
	v_min_u32_e32 v94, v90, v91
	v_min_u32_e32 v92, v88, v89
	v_min_u32_e32 v64, v68, v69
	v_max_u32_e32 v90, v90, v91
	v_max_u32_e32 v88, v88, v89
	v_max_u32_e32 v91, v70, v71
	v_max_u32_e32 v68, v68, v69
	v_min_u32_e32 v89, v90, v88
	v_min_u32_e32 v69, v91, v68
	v_max_u32_e32 v88, v90, v88
	v_max_u32_e32 v68, v91, v68
	v_max_u32_e32 v80, v74, v80
	v_max_u32_e32 v81, v75, v81
	v_max_u32_e32 v76, v72, v76
	v_max_u32_e32 v77, v73, v77
	v_max_u32_e32 v82, v82, v86
	v_max_u32_e32 v83, v83, v87
	v_max_u32_e32 v78, v78, v84
	v_max_u32_e32 v79, v79, v85
	v_min_u32_e32 v95, v70, v71
	v_min_u32_e32 v71, v89, v69
	v_max_u32_e32 v70, v89, v69
	v_min_u32_e32 v69, v88, v68
	v_max_u32_e32 v68, v88, v68
	v_min_u32_e32 v88, v80, v81
	v_min_u32_e32 v72, v76, v77
	v_min_u32_e32 v86, v82, v83
	v_max_u32_e32 v80, v80, v81
	v_max_u32_e32 v76, v76, v77
	v_max_u32_e32 v81, v82, v83
	v_max_u32_e32 v82, v78, v79
	v_min_u32_e32 v84, v78, v79
	v_min_u32_e32 v77, v80, v76
	v_min_u32_e32 v78, v81, v82
	v_max_u32_e32 v76, v80, v76
	v_max_u32_e32 v80, v81, v82
	v_min_u32_e32 v79, v77, v78
	v_max_u32_e32 v78, v77, v78
	v_min_u32_e32 v77, v76, v80
	v_max_u32_e32 v76, v76, v80
	v_mov_b32_e32 v80, 0x11000
	v_min_u32_e32 v93, v94, v92
	v_min_u32_e32 v65, v95, v64
	v_max_u32_e32 v92, v94, v92
	v_max_u32_e32 v64, v95, v64
	v_min_u32_e32 v73, v88, v72
	v_min_u32_e32 v74, v86, v84
	v_max_u32_e32 v72, v88, v72
	v_max_u32_e32 v84, v86, v84
	v_lshl_add_u32 v80, v128, 6, v80
	v_min_u32_e32 v67, v93, v65
	v_max_u32_e32 v66, v93, v65
	v_min_u32_e32 v65, v92, v64
	v_max_u32_e32 v64, v92, v64
	v_min_u32_e32 v75, v73, v74
	v_max_u32_e32 v74, v73, v74
	v_min_u32_e32 v73, v72, v84
	v_max_u32_e32 v72, v72, v84
	ds_write_b128 v80, v[76:79]
	ds_write_b128 v80, v[72:75] offset:16
	ds_write_b128 v80, v[68:71] offset:32
	ds_write_b128 v80, v[64:67] offset:48

.Lflush_f5:
	ds_read_b128 v[12:15], v249
	ds_read_b128 v[16:19], v249 offset:4224
	ds_read_b128 v[20:23], v249 offset:8448
	ds_read_b128 v[24:27], v249 offset:12672
	ds_read_b128 v[28:31], v249 offset:16896
	ds_read_b128 v[32:35], v249 offset:21120
	ds_read_b128 v[36:39], v249 offset:25344
	ds_read_b128 v[40:43], v249 offset:29568
	v_add_u32_e32 v249, 0x8400, v249
	s_waitcnt lgkmcnt(7)
	global_store_dwordx4 v[10:11], v[12:15], off
	s_waitcnt lgkmcnt(6)
	global_store_dwordx4 v[44:45], v[16:19], off
	s_waitcnt lgkmcnt(5)
	global_store_dwordx4 v[46:47], v[20:23], off
	s_waitcnt lgkmcnt(4)
	global_store_dwordx4 v[48:49], v[24:27], off
	s_waitcnt lgkmcnt(3)
	global_store_dwordx4 v[50:51], v[28:31], off
	s_waitcnt lgkmcnt(2)
	global_store_dwordx4 v[52:53], v[32:35], off
	s_waitcnt lgkmcnt(1)
	global_store_dwordx4 v[54:55], v[36:39], off
	s_waitcnt lgkmcnt(0)
	global_store_dwordx4 v[56:57], v[40:43], off
	v_lshl_add_u64 v[10:11], v[10:11], 0, v[58:59]
	v_lshl_add_u64 v[44:45], v[44:45], 0, v[58:59]
	v_lshl_add_u64 v[46:47], v[46:47], 0, v[58:59]
	v_lshl_add_u64 v[48:49], v[48:49], 0, v[58:59]
	v_lshl_add_u64 v[50:51], v[50:51], 0, v[58:59]
	v_lshl_add_u64 v[52:53], v[52:53], 0, v[58:59]
	v_lshl_add_u64 v[54:55], v[54:55], 0, v[58:59]
	v_lshl_add_u64 v[56:57], v[56:57], 0, v[58:59]
	s_add_i32 s4, s4, 1
	s_cmp_lt_u32 s4, 4
	s_cbranch_scc1 .Lflush_f5

.LBB0_225:
	v_ashrrev_i32_e32 v250, 5, v2
	v_mul_u32_u24_e32 v249, 0x210, v250
	v_add_u32_e32 v249, v249, v94
	v_lshlrev_b32_e32 v58, 12, v250
	v_mov_b32_e32 v59, 0
	v_lshl_add_u64 v[10:11], v[0:1], 0, v[58:59]
	v_mov_b32_e32 v58, 0x8000
	v_lshl_add_u64 v[44:45], v[10:11], 0, v[58:59]
	v_lshl_add_u64 v[46:47], v[44:45], 0, v[58:59]
	v_lshl_add_u64 v[48:49], v[46:47], 0, v[58:59]
	v_lshl_add_u64 v[50:51], v[48:49], 0, v[58:59]
	v_lshl_add_u64 v[52:53], v[50:51], 0, v[58:59]
	v_lshl_add_u64 v[54:55], v[52:53], 0, v[58:59]
	v_lshl_add_u64 v[56:57], v[54:55], 0, v[58:59]
	v_mov_b32_e32 v58, 0x40000
	s_mov_b32 s4, 0
.Lflush_f7:
	ds_read_b128 v[12:15], v249
	ds_read_b128 v[16:19], v249 offset:4224
	ds_read_b128 v[20:23], v249 offset:8448
	ds_read_b128 v[24:27], v249 offset:12672
	ds_read_b128 v[28:31], v249 offset:16896
	ds_read_b128 v[32:35], v249 offset:21120
	ds_read_b128 v[36:39], v249 offset:25344
	ds_read_b128 v[40:43], v249 offset:29568
	v_add_u32_e32 v249, 0x8400, v249
	s_waitcnt lgkmcnt(7)
	global_store_dwordx4 v[10:11], v[12:15], off
	s_waitcnt lgkmcnt(6)
	global_store_dwordx4 v[44:45], v[16:19], off
	s_waitcnt lgkmcnt(5)
	global_store_dwordx4 v[46:47], v[20:23], off
	s_waitcnt lgkmcnt(4)
	global_store_dwordx4 v[48:49], v[24:27], off
	s_waitcnt lgkmcnt(3)
	global_store_dwordx4 v[50:51], v[28:31], off
	s_waitcnt lgkmcnt(2)
	global_store_dwordx4 v[52:53], v[32:35], off
	s_waitcnt lgkmcnt(1)
	global_store_dwordx4 v[54:55], v[36:39], off
	s_waitcnt lgkmcnt(0)
	global_store_dwordx4 v[56:57], v[40:43], off
	v_lshl_add_u64 v[10:11], v[10:11], 0, v[58:59]
	v_lshl_add_u64 v[44:45], v[44:45], 0, v[58:59]
	v_lshl_add_u64 v[46:47], v[46:47], 0, v[58:59]
	v_lshl_add_u64 v[48:49], v[48:49], 0, v[58:59]
	v_lshl_add_u64 v[50:51], v[50:51], 0, v[58:59]
	v_lshl_add_u64 v[52:53], v[52:53], 0, v[58:59]
	v_lshl_add_u64 v[54:55], v[54:55], 0, v[58:59]
	v_lshl_add_u64 v[56:57], v[56:57], 0, v[58:59]
	s_add_i32 s4, s4, 1
	s_cmp_lt_u32 s4, 4
	s_cbranch_scc1 .Lflush_f7
	s_branch .LBB0_204
